# scan state stays resident in registers across chunks: per-chunk state copy-in/copy-out removed, zeroed once per item
# speedup vs baseline: 1.0235x; 1.0040x over previous
; #define LAS __attribute__((address_space(3)))
; DI unsigned pack2(float lo, float hi) { f32x2 v = {lo, hi}; return __builtin_bit_cast(unsigned, __builtin_convertvector(v, bf16x2_t)); }
; DI void scan_item(PP p, int l, int item, LAS unsigned char* lds) {
;     ...
;     f32x2 S[4];
; #pragma unroll
;     for (int j = 0; j < 4; ++j) S[j] = (f32x2){0.f, 0.f};
;     const int ks = lane & 7, vrow = half * 32 + (wid & 3) * 8 + (lane >> 3);
;     u16* Yp = Y + h * 64 + vrow;
;     LAS float* ypl = (LAS float*)(lds + 98304) + (wid & 3) * (8 * 68) + lane;
;     __syncthreads();
;     if (wid >= 4) { gl(0); fill(0); gl(1); }
;     __syncthreads();
;     ...
;     for (int c = 0; c < NCH; ++c) {
;         if (wid >= 4) { if (c + 1 < NCH) { fill(c + 1); if (c + 2 < NCH) gl(c + 2); } }
;         else {
;             const LAS float* sp = buf + ((c & 1) * T) * 384;
;             f32x4 Ar0, Ar1, Aw0, Aw1, Ak0, Ak1, Aa0, Aa1, Ab0, Ab1; float Avv;
;             f32x4 Br0, Br1, Bw0, Bw1, Bk0, Bk1, Ba0, Ba1, Bb0, Bb1; float Bvv;
;             SC_LD(A, sp);
;             const ptrdiff_t ystep = dir ? -512 : 512;
;             u16* Yl = Yp + (size_t)steprow(b, dir, c * T) * 512 + (ptrdiff_t)ks * ystep;
; #pragma nounroll
;             for (int st = 0; st < T; st += 2) {
;                 SC_LD(B, sp + (st + 1) * 384);
;                 SC_STEP(A, st);
;                 if (st + 2 < T) SC_LD(A, sp + (st + 2) * 384);
;                 SC_STEP(B, st + 1);
;                 if ((st & 6) == 6) {
;                     const LAS float* rp = ypl + (ks * 68 - lane) + (lane & ~7);
;                     const f32x4 q0 = *(const LAS f32x4*)rp, q1 = *(const LAS f32x4*)(rp + 4);
;                     Yl[(ptrdiff_t)(st - 6) * ystep] = (u16)(pack2(((q0[0] + q0[1]) + (q0[2] + q0[3])) + ((q1[0] + q1[1]) + (q1[2] + q1[3])), 0.f) & 0xffffu);
;                 }
;             }
;         }
;         __syncthreads();
;     }
.LBB0_250:
	s_add_u32 s6, s26, s53
	s_addc_u32 s7, s27, 0
	s_lshl_b32 s30, s49, 5
	s_and_b32 s50, s30, 32
	s_and_b32 s30, s41, 3
	s_lshl_b32 s51, s30, 3
	s_or_b32 s31, s51, s50
	v_lshrrev_b32_e32 v7, 3, v1
	s_lshl_b32 s9, s9, 1
	v_or_b32_e32 v136, s31, v7
	s_add_u32 s6, s6, s9
	s_addc_u32 s7, s7, 0
	v_lshlrev_b32_e32 v2, 1, v136
	v_mov_b32_e32 v3, v97
	s_mulk_i32 s30, 0x880
	v_lshl_add_u64 v[2:3], s[6:7], 0, v[2:3]
	s_add_i32 s6, s30, 0
	s_add_i32 s9, s6, 0x18000
	s_cmp_eq_u32 s8, 0
	s_cselect_b64 s[46:47], -1, 0
	s_and_b64 s[6:7], s[46:47], exec
	s_movk_i32 s6, 0xfe00
	v_and_b32_e32 v6, 7, v0
	s_cselect_b32 s41, 0x200, s6
	s_cselect_b32 s31, 0, -1
	s_lshl_b32 s53, s24, 11
	v_mul_hi_i32_i24_e32 v5, s41, v6
	v_mul_i32_i24_e32 v4, s41, v6
	v_and_b32_e32 v0, 56, v0
	s_addk_i32 s53, 0x800
	s_lshl_b32 s24, s24, 8
	v_lshl_add_u64 v[80:81], v[4:5], 1, v[2:3]
	v_mul_u32_u24_e32 v2, 0x110, v6
	v_lshlrev_b32_e32 v0, 2, v0
	s_add_i32 s54, s52, 32
	v_add3_u32 v139, s9, v2, v0
	s_and_b64 s[6:7], s[46:47], exec
	v_or_b32_e32 v0, s50, v7
	v_lshlrev_b32_e32 v1, 2, v1
	s_cselect_b32 s55, 1, -1
	s_cselect_b32 s56, 2, -2
	s_cselect_b32 s57, 3, -3
	s_cselect_b32 s58, 4, -4
	s_cselect_b32 s59, 5, -5
	s_cselect_b32 s60, 6, -6
	s_cselect_b32 s61, 7, -7
	v_or_b32_e32 v0, s51, v0
	v_readlane_b32 s3, v251, 45
	s_add_i32 s6, 0, 0x600
	v_add_u32_e32 v137, s9, v1
	v_lshlrev_b32_e32 v138, 3, v6
	s_mov_b32 s30, 0
	v_add_u32_e32 v140, 0, v1
	v_lshl_add_u32 v142, v0, 2, s3
	v_lshl_add_u32 v143, v6, 5, s6
	v_mov_b32_e32 v120, 0
	s_mov_b64 s[50:51], 0
	v_mov_b32_e32 v121, 0
	v_mov_b32_e32 v122, 0
	v_mov_b32_e32 v123, 0
	v_mov_b32_e32 v124, 0
	v_mov_b32_e32 v125, 0
	v_mov_b32_e32 v126, 0
	v_mov_b32_e32 v127, 0
	s_waitcnt lgkmcnt(0)
	s_barrier
	s_branch .LBB0_253
.LBB0_251:
.LBB0_252:
	s_add_i32 s30, s30, 1
	s_xor_b64 s[50:51], s[50:51], -1
	s_cmpk_lg_i32 s30, 0x48
	s_waitcnt lgkmcnt(0)
	s_barrier
	s_cbranch_scc0 .LBB0_237

; #define LAS __attribute__((address_space(3)))
; DI unsigned pack2(float lo, float hi) { f32x2 v = {lo, hi}; return __builtin_bit_cast(unsigned, __builtin_convertvector(v, bf16x2_t)); }
; DI void scan_item(PP p, int l, int item, LAS unsigned char* lds) {
;     ...
;             const LAS float* sp = buf + ((c & 1) * T) * 384;
;             f32x4 Ar0, Ar1, Aw0, Aw1, Ak0, Ak1, Aa0, Aa1, Ab0, Ab1; float Avv;
;             f32x4 Br0, Br1, Bw0, Bw1, Bk0, Bk1, Ba0, Ba1, Bb0, Bb1; float Bvv;
;             SC_LD(A, sp);
;             const ptrdiff_t ystep = dir ? -512 : 512;
;             u16* Yl = Yp + (size_t)steprow(b, dir, c * T) * 512 + (ptrdiff_t)ks * ystep;
; #pragma nounroll
;             for (int st = 0; st < T; st += 2) {
;                 SC_LD(B, sp + (st + 1) * 384);
;                 SC_STEP(A, st);
;                 if (st + 2 < T) SC_LD(A, sp + (st + 2) * 384);
;                 SC_STEP(B, st + 1);
;                 if ((st & 6) == 6) {
;                     const LAS float* rp = ypl + (ks * 68 - lane) + (lane & ~7);
;                     const f32x4 q0 = *(const LAS f32x4*)rp, q1 = *(const LAS f32x4*)(rp + 4);
;                     Yl[(ptrdiff_t)(st - 6) * ystep] = (u16)(pack2(((q0[0] + q0[1]) + (q0[2] + q0[3])) + ((q1[0] + q1[1]) + (q1[2] + q1[3])), 0.f) & 0xffffu);
;                 }
.Lscan_row_done:
	s_ashr_i32 s7, s6, 31
	s_lshl_b64 s[6:7], s[6:7], 10
	v_lshl_add_u64 v[118:119], v[80:81], 0, s[6:7]
	s_lshl_b32 s8, s41, 4
	s_mov_b32 s9, s31
	ds_read_b128 v[40:43], v154 offset:1536
	ds_read_b128 v[44:47], v154 offset:1552
	ds_read_b128 v[64:67], v154 offset:2304
	ds_read_b128 v[68:71], v154 offset:2320
	ds_read_b128 v[56:59], v154 offset:2048
	ds_read_b128 v[60:63], v154 offset:2064
	ds_read_b128 v[72:75], v154 offset:2560
	ds_read_b128 v[76:79], v154 offset:2576
	s_waitcnt lgkmcnt(8)
	v_pk_mul_f32 v[156:157], v[24:25], v[126:127]
	v_pk_mul_f32 v[90:91], v[28:29], v[122:123]
	v_pk_fma_f32 v[126:127], v[92:93], v[16:17], v[126:127] op_sel_hi:[0,1,1]
	v_pk_fma_f32 v[156:157], v[124:125], v[26:27], v[156:157]
	v_pk_fma_f32 v[90:91], v[120:121], v[30:31], v[90:91]
	v_pk_fma_f32 v[124:125], v[92:93], v[18:19], v[124:125] op_sel_hi:[0,1,1]
	v_pk_fma_f32 v[122:123], v[92:93], v[20:21], v[122:123] op_sel_hi:[0,1,1]
	v_pk_add_f32 v[156:157], v[156:157], v[90:91]
	v_pk_fma_f32 v[120:121], v[92:93], v[22:23], v[120:121] op_sel_hi:[0,1,1]
	v_add_f32_e32 v155, v156, v157
	s_nop 1
	v_add_f32_dpp v155, v155, v155 quad_perm:[1,0,3,2] row_mask:0xf bank_mask:0xf bound_ctrl:1
	s_nop 1
	v_add_f32_dpp v155, v155, v155 quad_perm:[2,3,0,1] row_mask:0xf bank_mask:0xf bound_ctrl:1
	s_nop 1
	v_add_f32_dpp v156, v155, v155 row_half_mirror row_mask:0xf bank_mask:0xf bound_ctrl:1
	v_pk_fma_f32 v[126:127], v[156:157], v[32:33], v[126:127] op_sel_hi:[0,1,1]
	v_pk_fma_f32 v[124:125], v[156:157], v[34:35], v[124:125] op_sel_hi:[0,1,1]
	v_pk_fma_f32 v[122:123], v[156:157], v[36:37], v[122:123] op_sel_hi:[0,1,1]
	v_pk_fma_f32 v[120:121], v[156:157], v[38:39], v[120:121] op_sel_hi:[0,1,1]
	ds_read_b128 v[24:27], v154 offset:3840
	ds_read_b128 v[28:31], v154 offset:3856
	ds_read_b128 v[16:19], v154 offset:3584
	ds_read_b128 v[20:23], v154 offset:3600
	ds_read_b128 v[32:35], v154 offset:4096
	ds_read_b128 v[36:39], v154 offset:4112
	ds_read2st64_b32 v[98:99], v153 offset0:17 offset1:23
	s_waitcnt lgkmcnt(7)
	v_pk_mul_f32 v[156:157], v[64:65], v[126:127]
	v_pk_mul_f32 v[90:91], v[68:69], v[122:123]
	v_pk_mul_f32 v[158:159], v[0:1], v[126:127]
	v_pk_fma_f32 v[156:157], v[124:125], v[66:67], v[156:157]
	v_pk_fma_f32 v[90:91], v[120:121], v[70:71], v[90:91]
	v_pk_fma_f32 v[158:159], v[124:125], v[2:3], v[158:159]
	v_pk_fma_f32 v[126:127], v[92:93], v[56:57], v[126:127] op_sel:[1,0,0] op_sel_hi:[1,1,1]
	v_pk_fma_f32 v[158:159], v[122:123], v[4:5], v[158:159]
	v_pk_fma_f32 v[124:125], v[92:93], v[58:59], v[124:125] op_sel:[1,0,0] op_sel_hi:[1,1,1]
	v_pk_add_f32 v[156:157], v[156:157], v[90:91]
	v_pk_fma_f32 v[158:159], v[120:121], v[6:7], v[158:159]
	v_add_f32_e32 v155, v156, v157
	v_pk_fma_f32 v[122:123], v[92:93], v[60:61], v[122:123] op_sel:[1,0,0] op_sel_hi:[1,1,1]
	v_pk_fma_f32 v[120:121], v[92:93], v[62:63], v[120:121] op_sel:[1,0,0] op_sel_hi:[1,1,1]
	ds_read_b128 v[0:3], v154 offset:3072
	ds_read_b128 v[4:7], v154 offset:3088
	v_add_f32_e32 v158, v158, v159
	v_add_f32_dpp v155, v155, v155 quad_perm:[1,0,3,2] row_mask:0xf bank_mask:0xf bound_ctrl:1
	s_mov_b32 s6, 0x1010101
	s_mov_b32 s7, 0x1010101
	v_add_f32_dpp v158, v158, v158 quad_perm:[1,0,3,2] row_mask:0xf bank_mask:0xf bound_ctrl:1
	v_add_f32_dpp v155, v155, v155 quad_perm:[2,3,0,1] row_mask:0xf bank_mask:0xf bound_ctrl:1
	s_nop 0
	v_add_f32_dpp v158, v158, v158 quad_perm:[2,3,0,1] row_mask:0xf bank_mask:0xf bound_ctrl:1
	v_add_f32_dpp v156, v155, v155 row_half_mirror row_mask:0xf bank_mask:0xf bound_ctrl:1
	v_pk_fma_f32 v[126:127], v[156:157], v[72:73], v[126:127] op_sel_hi:[0,1,1]
	v_pk_fma_f32 v[124:125], v[156:157], v[74:75], v[124:125] op_sel_hi:[0,1,1]
	v_add_f32_dpp v158, v158, v158 row_half_mirror row_mask:0xf bank_mask:0xf bound_ctrl:1
	v_pk_fma_f32 v[122:123], v[156:157], v[76:77], v[122:123] op_sel_hi:[0,1,1]
	v_pk_fma_f32 v[120:121], v[156:157], v[78:79], v[120:121] op_sel_hi:[0,1,1]
	v_cndmask_b32_e64 v94, v94, v158, s[6:7]
	ds_read_b128 v[64:67], v154 offset:5376
	ds_read_b128 v[68:71], v154 offset:5392
	ds_read_b128 v[56:59], v154 offset:5120
	ds_read_b128 v[60:63], v154 offset:5136
	ds_read_b128 v[72:75], v154 offset:5632
	ds_read_b128 v[76:79], v154 offset:5648
	s_waitcnt lgkmcnt(6)
	v_pk_mul_f32 v[156:157], v[24:25], v[126:127]
	v_pk_mul_f32 v[90:91], v[28:29], v[122:123]
	v_pk_mul_f32 v[158:159], v[40:41], v[126:127]
	v_pk_fma_f32 v[156:157], v[124:125], v[26:27], v[156:157]
	v_pk_fma_f32 v[90:91], v[120:121], v[30:31], v[90:91]
	v_pk_fma_f32 v[158:159], v[124:125], v[42:43], v[158:159]
	v_pk_fma_f32 v[126:127], v[98:99], v[16:17], v[126:127] op_sel_hi:[0,1,1]
	v_pk_fma_f32 v[158:159], v[122:123], v[44:45], v[158:159]
	v_pk_fma_f32 v[124:125], v[98:99], v[18:19], v[124:125] op_sel_hi:[0,1,1]
	v_pk_add_f32 v[156:157], v[156:157], v[90:91]
	v_pk_fma_f32 v[158:159], v[120:121], v[46:47], v[158:159]
	v_add_f32_e32 v155, v156, v157
	v_pk_fma_f32 v[122:123], v[98:99], v[20:21], v[122:123] op_sel_hi:[0,1,1]
	v_pk_fma_f32 v[120:121], v[98:99], v[22:23], v[120:121] op_sel_hi:[0,1,1]
	ds_read_b128 v[40:43], v154 offset:4608
	ds_read_b128 v[44:47], v154 offset:4624
	v_add_f32_e32 v158, v158, v159
	v_add_f32_dpp v155, v155, v155 quad_perm:[1,0,3,2] row_mask:0xf bank_mask:0xf bound_ctrl:1
	s_mov_b32 s6, 0x2020202
	s_mov_b32 s7, 0x2020202
	v_add_f32_dpp v158, v158, v158 quad_perm:[1,0,3,2] row_mask:0xf bank_mask:0xf bound_ctrl:1
	v_add_f32_dpp v155, v155, v155 quad_perm:[2,3,0,1] row_mask:0xf bank_mask:0xf bound_ctrl:1
	s_nop 0
	v_add_f32_dpp v158, v158, v158 quad_perm:[2,3,0,1] row_mask:0xf bank_mask:0xf bound_ctrl:1
	v_add_f32_dpp v156, v155, v155 row_half_mirror row_mask:0xf bank_mask:0xf bound_ctrl:1
	v_pk_fma_f32 v[126:127], v[156:157], v[32:33], v[126:127] op_sel_hi:[0,1,1]
	v_pk_fma_f32 v[124:125], v[156:157], v[34:35], v[124:125] op_sel_hi:[0,1,1]
	v_add_f32_dpp v158, v158, v158 row_half_mirror row_mask:0xf bank_mask:0xf bound_ctrl:1
	v_pk_fma_f32 v[122:123], v[156:157], v[36:37], v[122:123] op_sel_hi:[0,1,1]
	v_pk_fma_f32 v[120:121], v[156:157], v[38:39], v[120:121] op_sel_hi:[0,1,1]
	v_cndmask_b32_e64 v94, v94, v158, s[6:7]
	ds_read_b128 v[24:27], v154 offset:6912
	ds_read_b128 v[28:31], v154 offset:6928
	ds_read_b128 v[16:19], v154 offset:6656
	ds_read_b128 v[20:23], v154 offset:6672
	ds_read_b128 v[32:35], v154 offset:7168
	ds_read_b128 v[36:39], v154 offset:7184
	ds_read2st64_b32 v[92:93], v153 offset0:29 offset1:35
	s_waitcnt lgkmcnt(7)
; #define LAS __attribute__((address_space(3)))
; DI unsigned pack2(float lo, float hi) { f32x2 v = {lo, hi}; return __builtin_bit_cast(unsigned, __builtin_convertvector(v, bf16x2_t)); }
; DI void scan_item(PP p, int l, int item, LAS unsigned char* lds) {
;     ...
;     for (int c = 0; c < NCH; ++c) {
;         if (wid >= 4) { if (c + 1 < NCH) { fill(c + 1); if (c + 2 < NCH) gl(c + 2); } }
;         else {
;             const LAS float* sp = buf + ((c & 1) * T) * 384;
;             f32x4 Ar0, Ar1, Aw0, Aw1, Ak0, Ak1, Aa0, Aa1, Ab0, Ab1; float Avv;
;             f32x4 Br0, Br1, Bw0, Bw1, Bk0, Bk1, Ba0, Ba1, Bb0, Bb1; float Bvv;
;             SC_LD(A, sp);
;             const ptrdiff_t ystep = dir ? -512 : 512;
;             u16* Yl = Yp + (size_t)steprow(b, dir, c * T) * 512 + (ptrdiff_t)ks * ystep;
; #pragma nounroll
;             for (int st = 0; st < T; st += 2) {
;                 SC_LD(B, sp + (st + 1) * 384);
;                 SC_STEP(A, st);
;                 if (st + 2 < T) SC_LD(A, sp + (st + 2) * 384);
;                 SC_STEP(B, st + 1);
;                 if ((st & 6) == 6) {
;                     const LAS float* rp = ypl + (ks * 68 - lane) + (lane & ~7);
;                     const f32x4 q0 = *(const LAS f32x4*)rp, q1 = *(const LAS f32x4*)(rp + 4);
;                     Yl[(ptrdiff_t)(st - 6) * ystep] = (u16)(pack2(((q0[0] + q0[1]) + (q0[2] + q0[3])) + ((q1[0] + q1[1]) + (q1[2] + q1[3])), 0.f) & 0xffffu);
;                 }
	v_pk_mul_f32 v[156:157], v[64:65], v[126:127]
	v_pk_mul_f32 v[90:91], v[68:69], v[122:123]
	v_pk_mul_f32 v[158:159], v[0:1], v[126:127]
	v_pk_fma_f32 v[156:157], v[124:125], v[66:67], v[156:157]
	v_pk_fma_f32 v[90:91], v[120:121], v[70:71], v[90:91]
	v_pk_fma_f32 v[158:159], v[124:125], v[2:3], v[158:159]
	v_pk_fma_f32 v[126:127], v[98:99], v[56:57], v[126:127] op_sel:[1,0,0] op_sel_hi:[1,1,1]
	v_pk_fma_f32 v[158:159], v[122:123], v[4:5], v[158:159]
	v_pk_fma_f32 v[124:125], v[98:99], v[58:59], v[124:125] op_sel:[1,0,0] op_sel_hi:[1,1,1]
	v_pk_add_f32 v[156:157], v[156:157], v[90:91]
	v_pk_fma_f32 v[158:159], v[120:121], v[6:7], v[158:159]
	v_add_f32_e32 v155, v156, v157
	v_pk_fma_f32 v[122:123], v[98:99], v[60:61], v[122:123] op_sel:[1,0,0] op_sel_hi:[1,1,1]
	v_pk_fma_f32 v[120:121], v[98:99], v[62:63], v[120:121] op_sel:[1,0,0] op_sel_hi:[1,1,1]
	ds_read_b128 v[0:3], v154 offset:6144
	ds_read_b128 v[4:7], v154 offset:6160
	v_add_f32_e32 v158, v158, v159
	v_add_f32_dpp v155, v155, v155 quad_perm:[1,0,3,2] row_mask:0xf bank_mask:0xf bound_ctrl:1
	s_mov_b32 s6, 0x4040404
	s_mov_b32 s7, 0x4040404
	v_add_f32_dpp v158, v158, v158 quad_perm:[1,0,3,2] row_mask:0xf bank_mask:0xf bound_ctrl:1
	v_add_f32_dpp v155, v155, v155 quad_perm:[2,3,0,1] row_mask:0xf bank_mask:0xf bound_ctrl:1
	s_nop 0
	v_add_f32_dpp v158, v158, v158 quad_perm:[2,3,0,1] row_mask:0xf bank_mask:0xf bound_ctrl:1
	v_add_f32_dpp v156, v155, v155 row_half_mirror row_mask:0xf bank_mask:0xf bound_ctrl:1
	v_pk_fma_f32 v[126:127], v[156:157], v[72:73], v[126:127] op_sel_hi:[0,1,1]
	v_pk_fma_f32 v[124:125], v[156:157], v[74:75], v[124:125] op_sel_hi:[0,1,1]
	v_add_f32_dpp v158, v158, v158 row_half_mirror row_mask:0xf bank_mask:0xf bound_ctrl:1
	v_pk_fma_f32 v[122:123], v[156:157], v[76:77], v[122:123] op_sel_hi:[0,1,1]
	v_pk_fma_f32 v[120:121], v[156:157], v[78:79], v[120:121] op_sel_hi:[0,1,1]
	v_cndmask_b32_e64 v94, v94, v158, s[6:7]
	ds_read_b128 v[64:67], v154 offset:8448
	ds_read_b128 v[68:71], v154 offset:8464
	ds_read_b128 v[56:59], v154 offset:8192
	ds_read_b128 v[60:63], v154 offset:8208
	ds_read_b128 v[72:75], v154 offset:8704
	ds_read_b128 v[76:79], v154 offset:8720
	s_waitcnt lgkmcnt(6)
	v_pk_mul_f32 v[156:157], v[24:25], v[126:127]
	v_pk_mul_f32 v[90:91], v[28:29], v[122:123]
	v_pk_mul_f32 v[158:159], v[40:41], v[126:127]
	v_pk_fma_f32 v[156:157], v[124:125], v[26:27], v[156:157]
	v_pk_fma_f32 v[90:91], v[120:121], v[30:31], v[90:91]
	v_pk_fma_f32 v[158:159], v[124:125], v[42:43], v[158:159]
	v_pk_fma_f32 v[126:127], v[92:93], v[16:17], v[126:127] op_sel_hi:[0,1,1]
	v_pk_fma_f32 v[158:159], v[122:123], v[44:45], v[158:159]
	v_pk_fma_f32 v[124:125], v[92:93], v[18:19], v[124:125] op_sel_hi:[0,1,1]
	v_pk_add_f32 v[156:157], v[156:157], v[90:91]
	v_pk_fma_f32 v[158:159], v[120:121], v[46:47], v[158:159]
	v_add_f32_e32 v155, v156, v157
	v_pk_fma_f32 v[122:123], v[92:93], v[20:21], v[122:123] op_sel_hi:[0,1,1]
	v_pk_fma_f32 v[120:121], v[92:93], v[22:23], v[120:121] op_sel_hi:[0,1,1]
	ds_read_b128 v[40:43], v154 offset:7680
	ds_read_b128 v[44:47], v154 offset:7696
	v_add_f32_e32 v158, v158, v159
	v_add_f32_dpp v155, v155, v155 quad_perm:[1,0,3,2] row_mask:0xf bank_mask:0xf bound_ctrl:1
	s_mov_b32 s6, 0x8080808
	s_mov_b32 s7, 0x8080808
	v_add_f32_dpp v158, v158, v158 quad_perm:[1,0,3,2] row_mask:0xf bank_mask:0xf bound_ctrl:1
	v_add_f32_dpp v155, v155, v155 quad_perm:[2,3,0,1] row_mask:0xf bank_mask:0xf bound_ctrl:1
	s_nop 0
	v_add_f32_dpp v158, v158, v158 quad_perm:[2,3,0,1] row_mask:0xf bank_mask:0xf bound_ctrl:1
	v_add_f32_dpp v156, v155, v155 row_half_mirror row_mask:0xf bank_mask:0xf bound_ctrl:1
	v_pk_fma_f32 v[126:127], v[156:157], v[32:33], v[126:127] op_sel_hi:[0,1,1]
	v_pk_fma_f32 v[124:125], v[156:157], v[34:35], v[124:125] op_sel_hi:[0,1,1]
	v_add_f32_dpp v158, v158, v158 row_half_mirror row_mask:0xf bank_mask:0xf bound_ctrl:1
	v_pk_fma_f32 v[122:123], v[156:157], v[36:37], v[122:123] op_sel_hi:[0,1,1]
	v_pk_fma_f32 v[120:121], v[156:157], v[38:39], v[120:121] op_sel_hi:[0,1,1]
	v_cndmask_b32_e64 v94, v94, v158, s[6:7]
	ds_read_b128 v[24:27], v154 offset:9984
	ds_read_b128 v[28:31], v154 offset:10000
	ds_read_b128 v[16:19], v154 offset:9728
	ds_read_b128 v[20:23], v154 offset:9744
	ds_read_b128 v[32:35], v154 offset:10240
	ds_read_b128 v[36:39], v154 offset:10256
	ds_read2st64_b32 v[98:99], v153 offset0:41 offset1:47
	s_waitcnt lgkmcnt(7)
	v_pk_mul_f32 v[156:157], v[64:65], v[126:127]
	v_pk_mul_f32 v[90:91], v[68:69], v[122:123]
	v_pk_mul_f32 v[158:159], v[0:1], v[126:127]
	v_pk_fma_f32 v[156:157], v[124:125], v[66:67], v[156:157]
	v_pk_fma_f32 v[90:91], v[120:121], v[70:71], v[90:91]
	v_pk_fma_f32 v[158:159], v[124:125], v[2:3], v[158:159]
	v_pk_fma_f32 v[126:127], v[92:93], v[56:57], v[126:127] op_sel:[1,0,0] op_sel_hi:[1,1,1]
	v_pk_fma_f32 v[158:159], v[122:123], v[4:5], v[158:159]
	v_pk_fma_f32 v[124:125], v[92:93], v[58:59], v[124:125] op_sel:[1,0,0] op_sel_hi:[1,1,1]
	v_pk_add_f32 v[156:157], v[156:157], v[90:91]
	v_pk_fma_f32 v[158:159], v[120:121], v[6:7], v[158:159]
	v_add_f32_e32 v155, v156, v157
	v_pk_fma_f32 v[122:123], v[92:93], v[60:61], v[122:123] op_sel:[1,0,0] op_sel_hi:[1,1,1]
	v_pk_fma_f32 v[120:121], v[92:93], v[62:63], v[120:121] op_sel:[1,0,0] op_sel_hi:[1,1,1]
	ds_read_b128 v[0:3], v154 offset:9216
	ds_read_b128 v[4:7], v154 offset:9232
	v_add_f32_e32 v158, v158, v159
	v_add_f32_dpp v155, v155, v155 quad_perm:[1,0,3,2] row_mask:0xf bank_mask:0xf bound_ctrl:1
	s_mov_b32 s6, 0x10101010
	s_mov_b32 s7, 0x10101010
	v_add_f32_dpp v158, v158, v158 quad_perm:[1,0,3,2] row_mask:0xf bank_mask:0xf bound_ctrl:1
	v_add_f32_dpp v155, v155, v155 quad_perm:[2,3,0,1] row_mask:0xf bank_mask:0xf bound_ctrl:1
	s_nop 0
	v_add_f32_dpp v158, v158, v158 quad_perm:[2,3,0,1] row_mask:0xf bank_mask:0xf bound_ctrl:1
	v_add_f32_dpp v156, v155, v155 row_half_mirror row_mask:0xf bank_mask:0xf bound_ctrl:1
	v_pk_fma_f32 v[126:127], v[156:157], v[72:73], v[126:127] op_sel_hi:[0,1,1]
	v_pk_fma_f32 v[124:125], v[156:157], v[74:75], v[124:125] op_sel_hi:[0,1,1]
	v_add_f32_dpp v158, v158, v158 row_half_mirror row_mask:0xf bank_mask:0xf bound_ctrl:1
	v_pk_fma_f32 v[122:123], v[156:157], v[76:77], v[122:123] op_sel_hi:[0,1,1]
	v_pk_fma_f32 v[120:121], v[156:157], v[78:79], v[120:121] op_sel_hi:[0,1,1]
	v_cndmask_b32_e64 v94, v94, v158, s[6:7]
	ds_read_b128 v[64:67], v154 offset:11520
	ds_read_b128 v[68:71], v154 offset:11536
	ds_read_b128 v[56:59], v154 offset:11264
	ds_read_b128 v[60:63], v154 offset:11280
	ds_read_b128 v[72:75], v154 offset:11776
	ds_read_b128 v[76:79], v154 offset:11792
	ds_read_b128 v[48:51], v154 offset:11008
	ds_read_b128 v[52:55], v154 offset:11024
	s_waitcnt lgkmcnt(8)
; #define LAS __attribute__((address_space(3)))
; DI unsigned pack2(float lo, float hi) { f32x2 v = {lo, hi}; return __builtin_bit_cast(unsigned, __builtin_convertvector(v, bf16x2_t)); }
; DI void scan_item(PP p, int l, int item, LAS unsigned char* lds) {
;     ...
;     for (int c = 0; c < NCH; ++c) {
;         if (wid >= 4) { if (c + 1 < NCH) { fill(c + 1); if (c + 2 < NCH) gl(c + 2); } }
;         else {
;             const LAS float* sp = buf + ((c & 1) * T) * 384;
;             f32x4 Ar0, Ar1, Aw0, Aw1, Ak0, Ak1, Aa0, Aa1, Ab0, Ab1; float Avv;
;             f32x4 Br0, Br1, Bw0, Bw1, Bk0, Bk1, Ba0, Ba1, Bb0, Bb1; float Bvv;
;             SC_LD(A, sp);
;             const ptrdiff_t ystep = dir ? -512 : 512;
;             u16* Yl = Yp + (size_t)steprow(b, dir, c * T) * 512 + (ptrdiff_t)ks * ystep;
; #pragma nounroll
;             for (int st = 0; st < T; st += 2) {
;                 SC_LD(B, sp + (st + 1) * 384);
;                 SC_STEP(A, st);
;                 if (st + 2 < T) SC_LD(A, sp + (st + 2) * 384);
;                 SC_STEP(B, st + 1);
;                 if ((st & 6) == 6) {
;                     const LAS float* rp = ypl + (ks * 68 - lane) + (lane & ~7);
;                     const f32x4 q0 = *(const LAS f32x4*)rp, q1 = *(const LAS f32x4*)(rp + 4);
;                     Yl[(ptrdiff_t)(st - 6) * ystep] = (u16)(pack2(((q0[0] + q0[1]) + (q0[2] + q0[3])) + ((q1[0] + q1[1]) + (q1[2] + q1[3])), 0.f) & 0xffffu);
;                 }
	v_pk_mul_f32 v[156:157], v[24:25], v[126:127]
	v_pk_mul_f32 v[90:91], v[28:29], v[122:123]
	v_pk_mul_f32 v[158:159], v[40:41], v[126:127]
	v_pk_fma_f32 v[156:157], v[124:125], v[26:27], v[156:157]
	v_pk_fma_f32 v[90:91], v[120:121], v[30:31], v[90:91]
	v_pk_fma_f32 v[158:159], v[124:125], v[42:43], v[158:159]
	v_pk_fma_f32 v[126:127], v[98:99], v[16:17], v[126:127] op_sel_hi:[0,1,1]
	v_pk_fma_f32 v[158:159], v[122:123], v[44:45], v[158:159]
	v_pk_fma_f32 v[124:125], v[98:99], v[18:19], v[124:125] op_sel_hi:[0,1,1]
	v_pk_add_f32 v[156:157], v[156:157], v[90:91]
	v_pk_fma_f32 v[158:159], v[120:121], v[46:47], v[158:159]
	v_add_f32_e32 v155, v156, v157
	v_pk_fma_f32 v[122:123], v[98:99], v[20:21], v[122:123] op_sel_hi:[0,1,1]
	v_pk_fma_f32 v[120:121], v[98:99], v[22:23], v[120:121] op_sel_hi:[0,1,1]
	ds_read_b128 v[40:43], v154 offset:10752
	ds_read_b128 v[44:47], v154 offset:10768
	v_add_f32_e32 v158, v158, v159
	v_add_f32_dpp v155, v155, v155 quad_perm:[1,0,3,2] row_mask:0xf bank_mask:0xf bound_ctrl:1
	s_mov_b32 s6, 0x20202020
	s_mov_b32 s7, 0x20202020
	v_add_f32_dpp v158, v158, v158 quad_perm:[1,0,3,2] row_mask:0xf bank_mask:0xf bound_ctrl:1
	v_add_f32_dpp v155, v155, v155 quad_perm:[2,3,0,1] row_mask:0xf bank_mask:0xf bound_ctrl:1
	s_nop 0
	v_add_f32_dpp v158, v158, v158 quad_perm:[2,3,0,1] row_mask:0xf bank_mask:0xf bound_ctrl:1
	v_add_f32_dpp v156, v155, v155 row_half_mirror row_mask:0xf bank_mask:0xf bound_ctrl:1
	v_pk_fma_f32 v[126:127], v[156:157], v[32:33], v[126:127] op_sel_hi:[0,1,1]
	v_pk_fma_f32 v[124:125], v[156:157], v[34:35], v[124:125] op_sel_hi:[0,1,1]
	v_add_f32_dpp v158, v158, v158 row_half_mirror row_mask:0xf bank_mask:0xf bound_ctrl:1
	v_pk_fma_f32 v[122:123], v[156:157], v[36:37], v[122:123] op_sel_hi:[0,1,1]
	v_pk_fma_f32 v[120:121], v[156:157], v[38:39], v[120:121] op_sel_hi:[0,1,1]
	v_cndmask_b32_e64 v94, v94, v158, s[6:7]
	ds_read_b128 v[24:27], v154 offset:13056
	ds_read_b128 v[28:31], v154 offset:13072
	ds_read_b128 v[16:19], v154 offset:12800
	ds_read_b128 v[20:23], v154 offset:12816
	ds_read_b128 v[32:35], v154 offset:13312
	ds_read_b128 v[36:39], v154 offset:13328
	ds_read2st64_b32 v[92:93], v153 offset0:53 offset1:59
	s_waitcnt lgkmcnt(7)
	v_pk_mul_f32 v[156:157], v[64:65], v[126:127]
	v_pk_mul_f32 v[90:91], v[68:69], v[122:123]
	v_pk_mul_f32 v[158:159], v[0:1], v[126:127]
	v_pk_fma_f32 v[156:157], v[124:125], v[66:67], v[156:157]
	v_pk_fma_f32 v[90:91], v[120:121], v[70:71], v[90:91]
	v_pk_fma_f32 v[158:159], v[124:125], v[2:3], v[158:159]
	v_pk_fma_f32 v[126:127], v[98:99], v[56:57], v[126:127] op_sel:[1,0,0] op_sel_hi:[1,1,1]
	v_pk_fma_f32 v[158:159], v[122:123], v[4:5], v[158:159]
	v_pk_fma_f32 v[124:125], v[98:99], v[58:59], v[124:125] op_sel:[1,0,0] op_sel_hi:[1,1,1]
	v_pk_add_f32 v[156:157], v[156:157], v[90:91]
	v_pk_fma_f32 v[158:159], v[120:121], v[6:7], v[158:159]
	v_add_f32_e32 v155, v156, v157
	v_pk_fma_f32 v[122:123], v[98:99], v[60:61], v[122:123] op_sel:[1,0,0] op_sel_hi:[1,1,1]
	v_pk_fma_f32 v[120:121], v[98:99], v[62:63], v[120:121] op_sel:[1,0,0] op_sel_hi:[1,1,1]
	ds_read_b128 v[0:3], v154 offset:12288
	ds_read_b128 v[4:7], v154 offset:12304
	v_add_f32_e32 v158, v158, v159
	v_add_f32_dpp v155, v155, v155 quad_perm:[1,0,3,2] row_mask:0xf bank_mask:0xf bound_ctrl:1
	s_mov_b32 s6, 0x40404040
	s_mov_b32 s7, 0x40404040
	v_add_f32_dpp v158, v158, v158 quad_perm:[1,0,3,2] row_mask:0xf bank_mask:0xf bound_ctrl:1
	v_add_f32_dpp v155, v155, v155 quad_perm:[2,3,0,1] row_mask:0xf bank_mask:0xf bound_ctrl:1
	s_nop 0
	v_add_f32_dpp v158, v158, v158 quad_perm:[2,3,0,1] row_mask:0xf bank_mask:0xf bound_ctrl:1
	v_add_f32_dpp v156, v155, v155 row_half_mirror row_mask:0xf bank_mask:0xf bound_ctrl:1
	v_pk_fma_f32 v[126:127], v[156:157], v[72:73], v[126:127] op_sel_hi:[0,1,1]
	v_pk_fma_f32 v[124:125], v[156:157], v[74:75], v[124:125] op_sel_hi:[0,1,1]
	v_add_f32_dpp v158, v158, v158 row_half_mirror row_mask:0xf bank_mask:0xf bound_ctrl:1
	v_pk_fma_f32 v[122:123], v[156:157], v[76:77], v[122:123] op_sel_hi:[0,1,1]
	v_pk_fma_f32 v[120:121], v[156:157], v[78:79], v[120:121] op_sel_hi:[0,1,1]
	v_cndmask_b32_e64 v94, v94, v158, s[6:7]
	v_pk_mul_f32 v[158:159], v[40:41], v[126:127]
	s_nop 0
	v_pk_fma_f32 v[158:159], v[124:125], v[42:43], v[158:159]
	s_nop 0
	v_pk_fma_f32 v[158:159], v[122:123], v[44:45], v[158:159]
	s_nop 0
	v_pk_fma_f32 v[158:159], v[120:121], v[46:47], v[158:159]
	s_nop 0
	v_add_f32_e32 v158, v158, v159
	s_mov_b32 s6, 0x80808080
	s_mov_b32 s7, 0x80808080
	v_add_f32_dpp v158, v158, v158 quad_perm:[1,0,3,2] row_mask:0xf bank_mask:0xf bound_ctrl:1
	s_nop 1
	v_add_f32_dpp v158, v158, v158 quad_perm:[2,3,0,1] row_mask:0xf bank_mask:0xf bound_ctrl:1
	s_nop 1
	v_add_f32_dpp v158, v158, v158 row_half_mirror row_mask:0xf bank_mask:0xf bound_ctrl:1
	v_pk_mul_f32 v[126:127], v[48:49], v[126:127]
	v_pk_mul_f32 v[124:125], v[50:51], v[124:125]
	v_pk_mul_f32 v[122:123], v[52:53], v[122:123]
	v_pk_mul_f32 v[120:121], v[54:55], v[120:121]
	v_cndmask_b32_e64 v94, v94, v158, s[6:7]
	ds_read_b128 v[40:43], v154 offset:13824
	ds_read_b128 v[44:47], v154 offset:13840
	ds_read_b128 v[64:67], v154 offset:14592
	ds_read_b128 v[68:71], v154 offset:14608
	ds_read_b128 v[56:59], v154 offset:14336
	ds_read_b128 v[60:63], v154 offset:14352
	ds_read_b128 v[72:75], v154 offset:14848
	ds_read_b128 v[76:79], v154 offset:14864
	s_waitcnt lgkmcnt(8)
; #define LAS __attribute__((address_space(3)))
; DI unsigned pack2(float lo, float hi) { f32x2 v = {lo, hi}; return __builtin_bit_cast(unsigned, __builtin_convertvector(v, bf16x2_t)); }
; DI void scan_item(PP p, int l, int item, LAS unsigned char* lds) {
;     ...
;     for (int c = 0; c < NCH; ++c) {
;         if (wid >= 4) { if (c + 1 < NCH) { fill(c + 1); if (c + 2 < NCH) gl(c + 2); } }
;         else {
;             const LAS float* sp = buf + ((c & 1) * T) * 384;
;             f32x4 Ar0, Ar1, Aw0, Aw1, Ak0, Ak1, Aa0, Aa1, Ab0, Ab1; float Avv;
;             f32x4 Br0, Br1, Bw0, Bw1, Bk0, Bk1, Ba0, Ba1, Bb0, Bb1; float Bvv;
;             SC_LD(A, sp);
;             const ptrdiff_t ystep = dir ? -512 : 512;
;             u16* Yl = Yp + (size_t)steprow(b, dir, c * T) * 512 + (ptrdiff_t)ks * ystep;
; #pragma nounroll
;             for (int st = 0; st < T; st += 2) {
;                 SC_LD(B, sp + (st + 1) * 384);
;                 SC_STEP(A, st);
;                 if (st + 2 < T) SC_LD(A, sp + (st + 2) * 384);
;                 SC_STEP(B, st + 1);
;                 if ((st & 6) == 6) {
;                     const LAS float* rp = ypl + (ks * 68 - lane) + (lane & ~7);
;                     const f32x4 q0 = *(const LAS f32x4*)rp, q1 = *(const LAS f32x4*)(rp + 4);
;                     Yl[(ptrdiff_t)(st - 6) * ystep] = (u16)(pack2(((q0[0] + q0[1]) + (q0[2] + q0[3])) + ((q1[0] + q1[1]) + (q1[2] + q1[3])), 0.f) & 0xffffu);
;                 }
	v_pk_mul_f32 v[156:157], v[24:25], v[126:127]
	v_pk_mul_f32 v[90:91], v[28:29], v[122:123]
	v_pk_fma_f32 v[126:127], v[92:93], v[16:17], v[126:127] op_sel_hi:[0,1,1]
	v_pk_fma_f32 v[156:157], v[124:125], v[26:27], v[156:157]
	v_pk_fma_f32 v[90:91], v[120:121], v[30:31], v[90:91]
	v_pk_fma_f32 v[124:125], v[92:93], v[18:19], v[124:125] op_sel_hi:[0,1,1]
	v_pk_fma_f32 v[122:123], v[92:93], v[20:21], v[122:123] op_sel_hi:[0,1,1]
	v_pk_add_f32 v[156:157], v[156:157], v[90:91]
	v_pk_fma_f32 v[120:121], v[92:93], v[22:23], v[120:121] op_sel_hi:[0,1,1]
	v_add_f32_e32 v155, v156, v157
	s_nop 1
	v_add_f32_dpp v155, v155, v155 quad_perm:[1,0,3,2] row_mask:0xf bank_mask:0xf bound_ctrl:1
	s_nop 1
	v_add_f32_dpp v155, v155, v155 quad_perm:[2,3,0,1] row_mask:0xf bank_mask:0xf bound_ctrl:1
	s_nop 1
	v_add_f32_dpp v156, v155, v155 row_half_mirror row_mask:0xf bank_mask:0xf bound_ctrl:1
	v_pk_fma_f32 v[126:127], v[156:157], v[32:33], v[126:127] op_sel_hi:[0,1,1]
	v_pk_fma_f32 v[124:125], v[156:157], v[34:35], v[124:125] op_sel_hi:[0,1,1]
	v_pk_fma_f32 v[122:123], v[156:157], v[36:37], v[122:123] op_sel_hi:[0,1,1]
	v_pk_fma_f32 v[120:121], v[156:157], v[38:39], v[120:121] op_sel_hi:[0,1,1]
	v_cvt_pk_bf16_f32 v82, v94, v94
	global_store_short v[118:119], v82, off
	v_lshl_add_u64 v[118:119], s[8:9], 0, v[118:119]
	ds_read_b128 v[24:27], v154 offset:16128
	ds_read_b128 v[28:31], v154 offset:16144
	ds_read_b128 v[16:19], v154 offset:15872
	ds_read_b128 v[20:23], v154 offset:15888
	ds_read_b128 v[32:35], v154 offset:16384
	ds_read_b128 v[36:39], v154 offset:16400
	ds_read2st64_b32 v[98:99], v153 offset0:65 offset1:71
	s_waitcnt lgkmcnt(7)
	v_pk_mul_f32 v[156:157], v[64:65], v[126:127]
	v_pk_mul_f32 v[90:91], v[68:69], v[122:123]
	v_pk_mul_f32 v[158:159], v[0:1], v[126:127]
	v_pk_fma_f32 v[156:157], v[124:125], v[66:67], v[156:157]
	v_pk_fma_f32 v[90:91], v[120:121], v[70:71], v[90:91]
	v_pk_fma_f32 v[158:159], v[124:125], v[2:3], v[158:159]
	v_pk_fma_f32 v[126:127], v[92:93], v[56:57], v[126:127] op_sel:[1,0,0] op_sel_hi:[1,1,1]
	v_pk_fma_f32 v[158:159], v[122:123], v[4:5], v[158:159]
	v_pk_fma_f32 v[124:125], v[92:93], v[58:59], v[124:125] op_sel:[1,0,0] op_sel_hi:[1,1,1]
	v_pk_add_f32 v[156:157], v[156:157], v[90:91]
	v_pk_fma_f32 v[158:159], v[120:121], v[6:7], v[158:159]
	v_add_f32_e32 v155, v156, v157
	v_pk_fma_f32 v[122:123], v[92:93], v[60:61], v[122:123] op_sel:[1,0,0] op_sel_hi:[1,1,1]
	v_pk_fma_f32 v[120:121], v[92:93], v[62:63], v[120:121] op_sel:[1,0,0] op_sel_hi:[1,1,1]
	ds_read_b128 v[0:3], v154 offset:15360
	ds_read_b128 v[4:7], v154 offset:15376
	v_add_f32_e32 v158, v158, v159
	v_add_f32_dpp v155, v155, v155 quad_perm:[1,0,3,2] row_mask:0xf bank_mask:0xf bound_ctrl:1
	s_mov_b32 s6, 0x1010101
	s_mov_b32 s7, 0x1010101
	v_add_f32_dpp v158, v158, v158 quad_perm:[1,0,3,2] row_mask:0xf bank_mask:0xf bound_ctrl:1
	v_add_f32_dpp v155, v155, v155 quad_perm:[2,3,0,1] row_mask:0xf bank_mask:0xf bound_ctrl:1
	s_nop 0
	v_add_f32_dpp v158, v158, v158 quad_perm:[2,3,0,1] row_mask:0xf bank_mask:0xf bound_ctrl:1
	v_add_f32_dpp v156, v155, v155 row_half_mirror row_mask:0xf bank_mask:0xf bound_ctrl:1
	v_pk_fma_f32 v[126:127], v[156:157], v[72:73], v[126:127] op_sel_hi:[0,1,1]
	v_pk_fma_f32 v[124:125], v[156:157], v[74:75], v[124:125] op_sel_hi:[0,1,1]
	v_add_f32_dpp v158, v158, v158 row_half_mirror row_mask:0xf bank_mask:0xf bound_ctrl:1
	v_pk_fma_f32 v[122:123], v[156:157], v[76:77], v[122:123] op_sel_hi:[0,1,1]
	v_pk_fma_f32 v[120:121], v[156:157], v[78:79], v[120:121] op_sel_hi:[0,1,1]
	v_cndmask_b32_e64 v94, v94, v158, s[6:7]
	ds_read_b128 v[64:67], v154 offset:17664
	ds_read_b128 v[68:71], v154 offset:17680
	ds_read_b128 v[56:59], v154 offset:17408
	ds_read_b128 v[60:63], v154 offset:17424
	ds_read_b128 v[72:75], v154 offset:17920
	ds_read_b128 v[76:79], v154 offset:17936
	s_waitcnt lgkmcnt(6)
	v_pk_mul_f32 v[156:157], v[24:25], v[126:127]
	v_pk_mul_f32 v[90:91], v[28:29], v[122:123]
	v_pk_mul_f32 v[158:159], v[40:41], v[126:127]
	v_pk_fma_f32 v[156:157], v[124:125], v[26:27], v[156:157]
	v_pk_fma_f32 v[90:91], v[120:121], v[30:31], v[90:91]
	v_pk_fma_f32 v[158:159], v[124:125], v[42:43], v[158:159]
	v_pk_fma_f32 v[126:127], v[98:99], v[16:17], v[126:127] op_sel_hi:[0,1,1]
	v_pk_fma_f32 v[158:159], v[122:123], v[44:45], v[158:159]
	v_pk_fma_f32 v[124:125], v[98:99], v[18:19], v[124:125] op_sel_hi:[0,1,1]
	v_pk_add_f32 v[156:157], v[156:157], v[90:91]
	v_pk_fma_f32 v[158:159], v[120:121], v[46:47], v[158:159]
	v_add_f32_e32 v155, v156, v157
	v_pk_fma_f32 v[122:123], v[98:99], v[20:21], v[122:123] op_sel_hi:[0,1,1]
	v_pk_fma_f32 v[120:121], v[98:99], v[22:23], v[120:121] op_sel_hi:[0,1,1]
	ds_read_b128 v[40:43], v154 offset:16896
	ds_read_b128 v[44:47], v154 offset:16912
	v_add_f32_e32 v158, v158, v159
	v_add_f32_dpp v155, v155, v155 quad_perm:[1,0,3,2] row_mask:0xf bank_mask:0xf bound_ctrl:1
	s_mov_b32 s6, 0x2020202
	s_mov_b32 s7, 0x2020202
	v_add_f32_dpp v158, v158, v158 quad_perm:[1,0,3,2] row_mask:0xf bank_mask:0xf bound_ctrl:1
	v_add_f32_dpp v155, v155, v155 quad_perm:[2,3,0,1] row_mask:0xf bank_mask:0xf bound_ctrl:1
	s_nop 0
	v_add_f32_dpp v158, v158, v158 quad_perm:[2,3,0,1] row_mask:0xf bank_mask:0xf bound_ctrl:1
	v_add_f32_dpp v156, v155, v155 row_half_mirror row_mask:0xf bank_mask:0xf bound_ctrl:1
	v_pk_fma_f32 v[126:127], v[156:157], v[32:33], v[126:127] op_sel_hi:[0,1,1]
	v_pk_fma_f32 v[124:125], v[156:157], v[34:35], v[124:125] op_sel_hi:[0,1,1]
	v_add_f32_dpp v158, v158, v158 row_half_mirror row_mask:0xf bank_mask:0xf bound_ctrl:1
	v_pk_fma_f32 v[122:123], v[156:157], v[36:37], v[122:123] op_sel_hi:[0,1,1]
	v_pk_fma_f32 v[120:121], v[156:157], v[38:39], v[120:121] op_sel_hi:[0,1,1]
	v_cndmask_b32_e64 v94, v94, v158, s[6:7]
	ds_read_b128 v[24:27], v154 offset:19200
	ds_read_b128 v[28:31], v154 offset:19216
	ds_read_b128 v[16:19], v154 offset:18944
	ds_read_b128 v[20:23], v154 offset:18960
	ds_read_b128 v[32:35], v154 offset:19456
	ds_read_b128 v[36:39], v154 offset:19472
	ds_read2st64_b32 v[92:93], v153 offset0:77 offset1:83
	s_waitcnt lgkmcnt(7)
; #define LAS __attribute__((address_space(3)))
; DI unsigned pack2(float lo, float hi) { f32x2 v = {lo, hi}; return __builtin_bit_cast(unsigned, __builtin_convertvector(v, bf16x2_t)); }
; DI void scan_item(PP p, int l, int item, LAS unsigned char* lds) {
;     ...
;     for (int c = 0; c < NCH; ++c) {
;         if (wid >= 4) { if (c + 1 < NCH) { fill(c + 1); if (c + 2 < NCH) gl(c + 2); } }
;         else {
;             const LAS float* sp = buf + ((c & 1) * T) * 384;
;             f32x4 Ar0, Ar1, Aw0, Aw1, Ak0, Ak1, Aa0, Aa1, Ab0, Ab1; float Avv;
;             f32x4 Br0, Br1, Bw0, Bw1, Bk0, Bk1, Ba0, Ba1, Bb0, Bb1; float Bvv;
;             SC_LD(A, sp);
;             const ptrdiff_t ystep = dir ? -512 : 512;
;             u16* Yl = Yp + (size_t)steprow(b, dir, c * T) * 512 + (ptrdiff_t)ks * ystep;
; #pragma nounroll
;             for (int st = 0; st < T; st += 2) {
;                 SC_LD(B, sp + (st + 1) * 384);
;                 SC_STEP(A, st);
;                 if (st + 2 < T) SC_LD(A, sp + (st + 2) * 384);
;                 SC_STEP(B, st + 1);
;                 if ((st & 6) == 6) {
;                     const LAS float* rp = ypl + (ks * 68 - lane) + (lane & ~7);
;                     const f32x4 q0 = *(const LAS f32x4*)rp, q1 = *(const LAS f32x4*)(rp + 4);
;                     Yl[(ptrdiff_t)(st - 6) * ystep] = (u16)(pack2(((q0[0] + q0[1]) + (q0[2] + q0[3])) + ((q1[0] + q1[1]) + (q1[2] + q1[3])), 0.f) & 0xffffu);
;                 }
	v_pk_mul_f32 v[156:157], v[64:65], v[126:127]
	v_pk_mul_f32 v[90:91], v[68:69], v[122:123]
	v_pk_mul_f32 v[158:159], v[0:1], v[126:127]
	v_pk_fma_f32 v[156:157], v[124:125], v[66:67], v[156:157]
	v_pk_fma_f32 v[90:91], v[120:121], v[70:71], v[90:91]
	v_pk_fma_f32 v[158:159], v[124:125], v[2:3], v[158:159]
	v_pk_fma_f32 v[126:127], v[98:99], v[56:57], v[126:127] op_sel:[1,0,0] op_sel_hi:[1,1,1]
	v_pk_fma_f32 v[158:159], v[122:123], v[4:5], v[158:159]
	v_pk_fma_f32 v[124:125], v[98:99], v[58:59], v[124:125] op_sel:[1,0,0] op_sel_hi:[1,1,1]
	v_pk_add_f32 v[156:157], v[156:157], v[90:91]
	v_pk_fma_f32 v[158:159], v[120:121], v[6:7], v[158:159]
	v_add_f32_e32 v155, v156, v157
	v_pk_fma_f32 v[122:123], v[98:99], v[60:61], v[122:123] op_sel:[1,0,0] op_sel_hi:[1,1,1]
	v_pk_fma_f32 v[120:121], v[98:99], v[62:63], v[120:121] op_sel:[1,0,0] op_sel_hi:[1,1,1]
	ds_read_b128 v[0:3], v154 offset:18432
	ds_read_b128 v[4:7], v154 offset:18448
	v_add_f32_e32 v158, v158, v159
	v_add_f32_dpp v155, v155, v155 quad_perm:[1,0,3,2] row_mask:0xf bank_mask:0xf bound_ctrl:1
	s_mov_b32 s6, 0x4040404
	s_mov_b32 s7, 0x4040404
	v_add_f32_dpp v158, v158, v158 quad_perm:[1,0,3,2] row_mask:0xf bank_mask:0xf bound_ctrl:1
	v_add_f32_dpp v155, v155, v155 quad_perm:[2,3,0,1] row_mask:0xf bank_mask:0xf bound_ctrl:1
	s_nop 0
	v_add_f32_dpp v158, v158, v158 quad_perm:[2,3,0,1] row_mask:0xf bank_mask:0xf bound_ctrl:1
	v_add_f32_dpp v156, v155, v155 row_half_mirror row_mask:0xf bank_mask:0xf bound_ctrl:1
	v_pk_fma_f32 v[126:127], v[156:157], v[72:73], v[126:127] op_sel_hi:[0,1,1]
	v_pk_fma_f32 v[124:125], v[156:157], v[74:75], v[124:125] op_sel_hi:[0,1,1]
	v_add_f32_dpp v158, v158, v158 row_half_mirror row_mask:0xf bank_mask:0xf bound_ctrl:1
	v_pk_fma_f32 v[122:123], v[156:157], v[76:77], v[122:123] op_sel_hi:[0,1,1]
	v_pk_fma_f32 v[120:121], v[156:157], v[78:79], v[120:121] op_sel_hi:[0,1,1]
	v_cndmask_b32_e64 v94, v94, v158, s[6:7]
	ds_read_b128 v[64:67], v154 offset:20736
	ds_read_b128 v[68:71], v154 offset:20752
	ds_read_b128 v[56:59], v154 offset:20480
	ds_read_b128 v[60:63], v154 offset:20496
	ds_read_b128 v[72:75], v154 offset:20992
	ds_read_b128 v[76:79], v154 offset:21008
	s_waitcnt lgkmcnt(6)
	v_pk_mul_f32 v[156:157], v[24:25], v[126:127]
	v_pk_mul_f32 v[90:91], v[28:29], v[122:123]
	v_pk_mul_f32 v[158:159], v[40:41], v[126:127]
	v_pk_fma_f32 v[156:157], v[124:125], v[26:27], v[156:157]
	v_pk_fma_f32 v[90:91], v[120:121], v[30:31], v[90:91]
	v_pk_fma_f32 v[158:159], v[124:125], v[42:43], v[158:159]
	v_pk_fma_f32 v[126:127], v[92:93], v[16:17], v[126:127] op_sel_hi:[0,1,1]
	v_pk_fma_f32 v[158:159], v[122:123], v[44:45], v[158:159]
	v_pk_fma_f32 v[124:125], v[92:93], v[18:19], v[124:125] op_sel_hi:[0,1,1]
	v_pk_add_f32 v[156:157], v[156:157], v[90:91]
	v_pk_fma_f32 v[158:159], v[120:121], v[46:47], v[158:159]
	v_add_f32_e32 v155, v156, v157
	v_pk_fma_f32 v[122:123], v[92:93], v[20:21], v[122:123] op_sel_hi:[0,1,1]
	v_pk_fma_f32 v[120:121], v[92:93], v[22:23], v[120:121] op_sel_hi:[0,1,1]
	ds_read_b128 v[40:43], v154 offset:19968
	ds_read_b128 v[44:47], v154 offset:19984
	v_add_f32_e32 v158, v158, v159
	v_add_f32_dpp v155, v155, v155 quad_perm:[1,0,3,2] row_mask:0xf bank_mask:0xf bound_ctrl:1
	s_mov_b32 s6, 0x8080808
	s_mov_b32 s7, 0x8080808
	v_add_f32_dpp v158, v158, v158 quad_perm:[1,0,3,2] row_mask:0xf bank_mask:0xf bound_ctrl:1
	v_add_f32_dpp v155, v155, v155 quad_perm:[2,3,0,1] row_mask:0xf bank_mask:0xf bound_ctrl:1
	s_nop 0
	v_add_f32_dpp v158, v158, v158 quad_perm:[2,3,0,1] row_mask:0xf bank_mask:0xf bound_ctrl:1
	v_add_f32_dpp v156, v155, v155 row_half_mirror row_mask:0xf bank_mask:0xf bound_ctrl:1
	v_pk_fma_f32 v[126:127], v[156:157], v[32:33], v[126:127] op_sel_hi:[0,1,1]
	v_pk_fma_f32 v[124:125], v[156:157], v[34:35], v[124:125] op_sel_hi:[0,1,1]
	v_add_f32_dpp v158, v158, v158 row_half_mirror row_mask:0xf bank_mask:0xf bound_ctrl:1
	v_pk_fma_f32 v[122:123], v[156:157], v[36:37], v[122:123] op_sel_hi:[0,1,1]
	v_pk_fma_f32 v[120:121], v[156:157], v[38:39], v[120:121] op_sel_hi:[0,1,1]
	v_cndmask_b32_e64 v94, v94, v158, s[6:7]
	ds_read_b128 v[24:27], v154 offset:22272
	ds_read_b128 v[28:31], v154 offset:22288
	ds_read_b128 v[16:19], v154 offset:22016
	ds_read_b128 v[20:23], v154 offset:22032
	ds_read_b128 v[32:35], v154 offset:22528
	ds_read_b128 v[36:39], v154 offset:22544
	ds_read2st64_b32 v[98:99], v153 offset0:89 offset1:95
	s_waitcnt lgkmcnt(7)
	v_pk_mul_f32 v[156:157], v[64:65], v[126:127]
	v_pk_mul_f32 v[90:91], v[68:69], v[122:123]
	v_pk_mul_f32 v[158:159], v[0:1], v[126:127]
	v_pk_fma_f32 v[156:157], v[124:125], v[66:67], v[156:157]
	v_pk_fma_f32 v[90:91], v[120:121], v[70:71], v[90:91]
	v_pk_fma_f32 v[158:159], v[124:125], v[2:3], v[158:159]
	v_pk_fma_f32 v[126:127], v[92:93], v[56:57], v[126:127] op_sel:[1,0,0] op_sel_hi:[1,1,1]
	v_pk_fma_f32 v[158:159], v[122:123], v[4:5], v[158:159]
	v_pk_fma_f32 v[124:125], v[92:93], v[58:59], v[124:125] op_sel:[1,0,0] op_sel_hi:[1,1,1]
	v_pk_add_f32 v[156:157], v[156:157], v[90:91]
	v_pk_fma_f32 v[158:159], v[120:121], v[6:7], v[158:159]
	v_add_f32_e32 v155, v156, v157
	v_pk_fma_f32 v[122:123], v[92:93], v[60:61], v[122:123] op_sel:[1,0,0] op_sel_hi:[1,1,1]
	v_pk_fma_f32 v[120:121], v[92:93], v[62:63], v[120:121] op_sel:[1,0,0] op_sel_hi:[1,1,1]
	ds_read_b128 v[0:3], v154 offset:21504
	ds_read_b128 v[4:7], v154 offset:21520
	v_add_f32_e32 v158, v158, v159
	v_add_f32_dpp v155, v155, v155 quad_perm:[1,0,3,2] row_mask:0xf bank_mask:0xf bound_ctrl:1
	s_mov_b32 s6, 0x10101010
	s_mov_b32 s7, 0x10101010
	v_add_f32_dpp v158, v158, v158 quad_perm:[1,0,3,2] row_mask:0xf bank_mask:0xf bound_ctrl:1
	v_add_f32_dpp v155, v155, v155 quad_perm:[2,3,0,1] row_mask:0xf bank_mask:0xf bound_ctrl:1
	s_nop 0
	v_add_f32_dpp v158, v158, v158 quad_perm:[2,3,0,1] row_mask:0xf bank_mask:0xf bound_ctrl:1
	v_add_f32_dpp v156, v155, v155 row_half_mirror row_mask:0xf bank_mask:0xf bound_ctrl:1
	v_pk_fma_f32 v[126:127], v[156:157], v[72:73], v[126:127] op_sel_hi:[0,1,1]
	v_pk_fma_f32 v[124:125], v[156:157], v[74:75], v[124:125] op_sel_hi:[0,1,1]
	v_add_f32_dpp v158, v158, v158 row_half_mirror row_mask:0xf bank_mask:0xf bound_ctrl:1
	v_pk_fma_f32 v[122:123], v[156:157], v[76:77], v[122:123] op_sel_hi:[0,1,1]
	v_pk_fma_f32 v[120:121], v[156:157], v[78:79], v[120:121] op_sel_hi:[0,1,1]
	v_cndmask_b32_e64 v94, v94, v158, s[6:7]
	ds_read_b128 v[64:67], v154 offset:23808
	ds_read_b128 v[68:71], v154 offset:23824
	ds_read_b128 v[56:59], v154 offset:23552
	ds_read_b128 v[60:63], v154 offset:23568
	ds_read_b128 v[72:75], v154 offset:24064
	ds_read_b128 v[76:79], v154 offset:24080
	ds_read_b128 v[48:51], v154 offset:23296
	ds_read_b128 v[52:55], v154 offset:23312
	s_waitcnt lgkmcnt(8)
; #define LAS __attribute__((address_space(3)))
; DI unsigned pack2(float lo, float hi) { f32x2 v = {lo, hi}; return __builtin_bit_cast(unsigned, __builtin_convertvector(v, bf16x2_t)); }
; DI void scan_item(PP p, int l, int item, LAS unsigned char* lds) {
;     ...
;     for (int c = 0; c < NCH; ++c) {
;         if (wid >= 4) { if (c + 1 < NCH) { fill(c + 1); if (c + 2 < NCH) gl(c + 2); } }
;         else {
;             const LAS float* sp = buf + ((c & 1) * T) * 384;
;             f32x4 Ar0, Ar1, Aw0, Aw1, Ak0, Ak1, Aa0, Aa1, Ab0, Ab1; float Avv;
;             f32x4 Br0, Br1, Bw0, Bw1, Bk0, Bk1, Ba0, Ba1, Bb0, Bb1; float Bvv;
;             SC_LD(A, sp);
;             const ptrdiff_t ystep = dir ? -512 : 512;
;             u16* Yl = Yp + (size_t)steprow(b, dir, c * T) * 512 + (ptrdiff_t)ks * ystep;
; #pragma nounroll
;             for (int st = 0; st < T; st += 2) {
;                 SC_LD(B, sp + (st + 1) * 384);
;                 SC_STEP(A, st);
;                 if (st + 2 < T) SC_LD(A, sp + (st + 2) * 384);
;                 SC_STEP(B, st + 1);
;                 if ((st & 6) == 6) {
;                     const LAS float* rp = ypl + (ks * 68 - lane) + (lane & ~7);
;                     const f32x4 q0 = *(const LAS f32x4*)rp, q1 = *(const LAS f32x4*)(rp + 4);
;                     Yl[(ptrdiff_t)(st - 6) * ystep] = (u16)(pack2(((q0[0] + q0[1]) + (q0[2] + q0[3])) + ((q1[0] + q1[1]) + (q1[2] + q1[3])), 0.f) & 0xffffu);
;                 }
	v_pk_mul_f32 v[156:157], v[24:25], v[126:127]
	v_pk_mul_f32 v[90:91], v[28:29], v[122:123]
	v_pk_mul_f32 v[158:159], v[40:41], v[126:127]
	v_pk_fma_f32 v[156:157], v[124:125], v[26:27], v[156:157]
	v_pk_fma_f32 v[90:91], v[120:121], v[30:31], v[90:91]
	v_pk_fma_f32 v[158:159], v[124:125], v[42:43], v[158:159]
	v_pk_fma_f32 v[126:127], v[98:99], v[16:17], v[126:127] op_sel_hi:[0,1,1]
	v_pk_fma_f32 v[158:159], v[122:123], v[44:45], v[158:159]
	v_pk_fma_f32 v[124:125], v[98:99], v[18:19], v[124:125] op_sel_hi:[0,1,1]
	v_pk_add_f32 v[156:157], v[156:157], v[90:91]
	v_pk_fma_f32 v[158:159], v[120:121], v[46:47], v[158:159]
	v_add_f32_e32 v155, v156, v157
	v_pk_fma_f32 v[122:123], v[98:99], v[20:21], v[122:123] op_sel_hi:[0,1,1]
	v_pk_fma_f32 v[120:121], v[98:99], v[22:23], v[120:121] op_sel_hi:[0,1,1]
	ds_read_b128 v[40:43], v154 offset:23040
	ds_read_b128 v[44:47], v154 offset:23056
	v_add_f32_e32 v158, v158, v159
	v_add_f32_dpp v155, v155, v155 quad_perm:[1,0,3,2] row_mask:0xf bank_mask:0xf bound_ctrl:1
	s_mov_b32 s6, 0x20202020
	s_mov_b32 s7, 0x20202020
	v_add_f32_dpp v158, v158, v158 quad_perm:[1,0,3,2] row_mask:0xf bank_mask:0xf bound_ctrl:1
	v_add_f32_dpp v155, v155, v155 quad_perm:[2,3,0,1] row_mask:0xf bank_mask:0xf bound_ctrl:1
	s_nop 0
	v_add_f32_dpp v158, v158, v158 quad_perm:[2,3,0,1] row_mask:0xf bank_mask:0xf bound_ctrl:1
	v_add_f32_dpp v156, v155, v155 row_half_mirror row_mask:0xf bank_mask:0xf bound_ctrl:1
	v_pk_fma_f32 v[126:127], v[156:157], v[32:33], v[126:127] op_sel_hi:[0,1,1]
	v_pk_fma_f32 v[124:125], v[156:157], v[34:35], v[124:125] op_sel_hi:[0,1,1]
	v_add_f32_dpp v158, v158, v158 row_half_mirror row_mask:0xf bank_mask:0xf bound_ctrl:1
	v_pk_fma_f32 v[122:123], v[156:157], v[36:37], v[122:123] op_sel_hi:[0,1,1]
	v_pk_fma_f32 v[120:121], v[156:157], v[38:39], v[120:121] op_sel_hi:[0,1,1]
	v_cndmask_b32_e64 v94, v94, v158, s[6:7]
	ds_read_b128 v[24:27], v154 offset:25344
	ds_read_b128 v[28:31], v154 offset:25360
	ds_read_b128 v[16:19], v154 offset:25088
	ds_read_b128 v[20:23], v154 offset:25104
	ds_read_b128 v[32:35], v154 offset:25600
	ds_read_b128 v[36:39], v154 offset:25616
	ds_read2st64_b32 v[92:93], v153 offset0:101 offset1:107
	s_waitcnt lgkmcnt(7)
	v_pk_mul_f32 v[156:157], v[64:65], v[126:127]
	v_pk_mul_f32 v[90:91], v[68:69], v[122:123]
	v_pk_mul_f32 v[158:159], v[0:1], v[126:127]
	v_pk_fma_f32 v[156:157], v[124:125], v[66:67], v[156:157]
	v_pk_fma_f32 v[90:91], v[120:121], v[70:71], v[90:91]
	v_pk_fma_f32 v[158:159], v[124:125], v[2:3], v[158:159]
	v_pk_fma_f32 v[126:127], v[98:99], v[56:57], v[126:127] op_sel:[1,0,0] op_sel_hi:[1,1,1]
	v_pk_fma_f32 v[158:159], v[122:123], v[4:5], v[158:159]
	v_pk_fma_f32 v[124:125], v[98:99], v[58:59], v[124:125] op_sel:[1,0,0] op_sel_hi:[1,1,1]
	v_pk_add_f32 v[156:157], v[156:157], v[90:91]
	v_pk_fma_f32 v[158:159], v[120:121], v[6:7], v[158:159]
	v_add_f32_e32 v155, v156, v157
	v_pk_fma_f32 v[122:123], v[98:99], v[60:61], v[122:123] op_sel:[1,0,0] op_sel_hi:[1,1,1]
	v_pk_fma_f32 v[120:121], v[98:99], v[62:63], v[120:121] op_sel:[1,0,0] op_sel_hi:[1,1,1]
	ds_read_b128 v[0:3], v154 offset:24576
	ds_read_b128 v[4:7], v154 offset:24592
	v_add_f32_e32 v158, v158, v159
	v_add_f32_dpp v155, v155, v155 quad_perm:[1,0,3,2] row_mask:0xf bank_mask:0xf bound_ctrl:1
	s_mov_b32 s6, 0x40404040
	s_mov_b32 s7, 0x40404040
	v_add_f32_dpp v158, v158, v158 quad_perm:[1,0,3,2] row_mask:0xf bank_mask:0xf bound_ctrl:1
	v_add_f32_dpp v155, v155, v155 quad_perm:[2,3,0,1] row_mask:0xf bank_mask:0xf bound_ctrl:1
	s_nop 0
	v_add_f32_dpp v158, v158, v158 quad_perm:[2,3,0,1] row_mask:0xf bank_mask:0xf bound_ctrl:1
	v_add_f32_dpp v156, v155, v155 row_half_mirror row_mask:0xf bank_mask:0xf bound_ctrl:1
	v_pk_fma_f32 v[126:127], v[156:157], v[72:73], v[126:127] op_sel_hi:[0,1,1]
	v_pk_fma_f32 v[124:125], v[156:157], v[74:75], v[124:125] op_sel_hi:[0,1,1]
	v_add_f32_dpp v158, v158, v158 row_half_mirror row_mask:0xf bank_mask:0xf bound_ctrl:1
	v_pk_fma_f32 v[122:123], v[156:157], v[76:77], v[122:123] op_sel_hi:[0,1,1]
	v_pk_fma_f32 v[120:121], v[156:157], v[78:79], v[120:121] op_sel_hi:[0,1,1]
	v_cndmask_b32_e64 v94, v94, v158, s[6:7]
	v_pk_mul_f32 v[158:159], v[40:41], v[126:127]
	s_nop 0
	v_pk_fma_f32 v[158:159], v[124:125], v[42:43], v[158:159]
	s_nop 0
	v_pk_fma_f32 v[158:159], v[122:123], v[44:45], v[158:159]
	s_nop 0
	v_pk_fma_f32 v[158:159], v[120:121], v[46:47], v[158:159]
	s_nop 0
	v_add_f32_e32 v158, v158, v159
	s_mov_b32 s6, 0x80808080
	s_mov_b32 s7, 0x80808080
	v_add_f32_dpp v158, v158, v158 quad_perm:[1,0,3,2] row_mask:0xf bank_mask:0xf bound_ctrl:1
	s_nop 1
	v_add_f32_dpp v158, v158, v158 quad_perm:[2,3,0,1] row_mask:0xf bank_mask:0xf bound_ctrl:1
	s_nop 1
	v_add_f32_dpp v158, v158, v158 row_half_mirror row_mask:0xf bank_mask:0xf bound_ctrl:1
	v_pk_mul_f32 v[126:127], v[48:49], v[126:127]
	v_pk_mul_f32 v[124:125], v[50:51], v[124:125]
	v_pk_mul_f32 v[122:123], v[52:53], v[122:123]
	v_pk_mul_f32 v[120:121], v[54:55], v[120:121]
	v_cndmask_b32_e64 v94, v94, v158, s[6:7]
	ds_read_b128 v[40:43], v154 offset:26112
	ds_read_b128 v[44:47], v154 offset:26128
	ds_read_b128 v[64:67], v154 offset:26880
	ds_read_b128 v[68:71], v154 offset:26896
	ds_read_b128 v[56:59], v154 offset:26624
	ds_read_b128 v[60:63], v154 offset:26640
	ds_read_b128 v[72:75], v154 offset:27136
	ds_read_b128 v[76:79], v154 offset:27152
	s_waitcnt lgkmcnt(8)
; #define LAS __attribute__((address_space(3)))
; DI unsigned pack2(float lo, float hi) { f32x2 v = {lo, hi}; return __builtin_bit_cast(unsigned, __builtin_convertvector(v, bf16x2_t)); }
; DI void scan_item(PP p, int l, int item, LAS unsigned char* lds) {
;     ...
;     for (int c = 0; c < NCH; ++c) {
;         if (wid >= 4) { if (c + 1 < NCH) { fill(c + 1); if (c + 2 < NCH) gl(c + 2); } }
;         else {
;             const LAS float* sp = buf + ((c & 1) * T) * 384;
;             f32x4 Ar0, Ar1, Aw0, Aw1, Ak0, Ak1, Aa0, Aa1, Ab0, Ab1; float Avv;
;             f32x4 Br0, Br1, Bw0, Bw1, Bk0, Bk1, Ba0, Ba1, Bb0, Bb1; float Bvv;
;             SC_LD(A, sp);
;             const ptrdiff_t ystep = dir ? -512 : 512;
;             u16* Yl = Yp + (size_t)steprow(b, dir, c * T) * 512 + (ptrdiff_t)ks * ystep;
; #pragma nounroll
;             for (int st = 0; st < T; st += 2) {
;                 SC_LD(B, sp + (st + 1) * 384);
;                 SC_STEP(A, st);
;                 if (st + 2 < T) SC_LD(A, sp + (st + 2) * 384);
;                 SC_STEP(B, st + 1);
;                 if ((st & 6) == 6) {
;                     const LAS float* rp = ypl + (ks * 68 - lane) + (lane & ~7);
;                     const f32x4 q0 = *(const LAS f32x4*)rp, q1 = *(const LAS f32x4*)(rp + 4);
;                     Yl[(ptrdiff_t)(st - 6) * ystep] = (u16)(pack2(((q0[0] + q0[1]) + (q0[2] + q0[3])) + ((q1[0] + q1[1]) + (q1[2] + q1[3])), 0.f) & 0xffffu);
;                 }
	v_pk_mul_f32 v[156:157], v[24:25], v[126:127]
	v_pk_mul_f32 v[90:91], v[28:29], v[122:123]
	v_pk_fma_f32 v[126:127], v[92:93], v[16:17], v[126:127] op_sel_hi:[0,1,1]
	v_pk_fma_f32 v[156:157], v[124:125], v[26:27], v[156:157]
	v_pk_fma_f32 v[90:91], v[120:121], v[30:31], v[90:91]
	v_pk_fma_f32 v[124:125], v[92:93], v[18:19], v[124:125] op_sel_hi:[0,1,1]
	v_pk_fma_f32 v[122:123], v[92:93], v[20:21], v[122:123] op_sel_hi:[0,1,1]
	v_pk_add_f32 v[156:157], v[156:157], v[90:91]
	v_pk_fma_f32 v[120:121], v[92:93], v[22:23], v[120:121] op_sel_hi:[0,1,1]
	v_add_f32_e32 v155, v156, v157
	s_nop 1
	v_add_f32_dpp v155, v155, v155 quad_perm:[1,0,3,2] row_mask:0xf bank_mask:0xf bound_ctrl:1
	s_nop 1
	v_add_f32_dpp v155, v155, v155 quad_perm:[2,3,0,1] row_mask:0xf bank_mask:0xf bound_ctrl:1
	s_nop 1
	v_add_f32_dpp v156, v155, v155 row_half_mirror row_mask:0xf bank_mask:0xf bound_ctrl:1
	v_pk_fma_f32 v[126:127], v[156:157], v[32:33], v[126:127] op_sel_hi:[0,1,1]
	v_pk_fma_f32 v[124:125], v[156:157], v[34:35], v[124:125] op_sel_hi:[0,1,1]
	v_pk_fma_f32 v[122:123], v[156:157], v[36:37], v[122:123] op_sel_hi:[0,1,1]
	v_pk_fma_f32 v[120:121], v[156:157], v[38:39], v[120:121] op_sel_hi:[0,1,1]
	v_cvt_pk_bf16_f32 v82, v94, v94
	global_store_short v[118:119], v82, off
	v_lshl_add_u64 v[118:119], s[8:9], 0, v[118:119]
	ds_read_b128 v[24:27], v154 offset:28416
	ds_read_b128 v[28:31], v154 offset:28432
	ds_read_b128 v[16:19], v154 offset:28160
	ds_read_b128 v[20:23], v154 offset:28176
	ds_read_b128 v[32:35], v154 offset:28672
	ds_read_b128 v[36:39], v154 offset:28688
	ds_read2st64_b32 v[98:99], v153 offset0:113 offset1:119
	s_waitcnt lgkmcnt(7)
	v_pk_mul_f32 v[156:157], v[64:65], v[126:127]
	v_pk_mul_f32 v[90:91], v[68:69], v[122:123]
	v_pk_mul_f32 v[158:159], v[0:1], v[126:127]
	v_pk_fma_f32 v[156:157], v[124:125], v[66:67], v[156:157]
	v_pk_fma_f32 v[90:91], v[120:121], v[70:71], v[90:91]
	v_pk_fma_f32 v[158:159], v[124:125], v[2:3], v[158:159]
	v_pk_fma_f32 v[126:127], v[92:93], v[56:57], v[126:127] op_sel:[1,0,0] op_sel_hi:[1,1,1]
	v_pk_fma_f32 v[158:159], v[122:123], v[4:5], v[158:159]
	v_pk_fma_f32 v[124:125], v[92:93], v[58:59], v[124:125] op_sel:[1,0,0] op_sel_hi:[1,1,1]
	v_pk_add_f32 v[156:157], v[156:157], v[90:91]
	v_pk_fma_f32 v[158:159], v[120:121], v[6:7], v[158:159]
	v_add_f32_e32 v155, v156, v157
	v_pk_fma_f32 v[122:123], v[92:93], v[60:61], v[122:123] op_sel:[1,0,0] op_sel_hi:[1,1,1]
	v_pk_fma_f32 v[120:121], v[92:93], v[62:63], v[120:121] op_sel:[1,0,0] op_sel_hi:[1,1,1]
	ds_read_b128 v[0:3], v154 offset:27648
	ds_read_b128 v[4:7], v154 offset:27664
	v_add_f32_e32 v158, v158, v159
	v_add_f32_dpp v155, v155, v155 quad_perm:[1,0,3,2] row_mask:0xf bank_mask:0xf bound_ctrl:1
	s_mov_b32 s6, 0x1010101
	s_mov_b32 s7, 0x1010101
	v_add_f32_dpp v158, v158, v158 quad_perm:[1,0,3,2] row_mask:0xf bank_mask:0xf bound_ctrl:1
	v_add_f32_dpp v155, v155, v155 quad_perm:[2,3,0,1] row_mask:0xf bank_mask:0xf bound_ctrl:1
	s_nop 0
	v_add_f32_dpp v158, v158, v158 quad_perm:[2,3,0,1] row_mask:0xf bank_mask:0xf bound_ctrl:1
	v_add_f32_dpp v156, v155, v155 row_half_mirror row_mask:0xf bank_mask:0xf bound_ctrl:1
	v_pk_fma_f32 v[126:127], v[156:157], v[72:73], v[126:127] op_sel_hi:[0,1,1]
	v_pk_fma_f32 v[124:125], v[156:157], v[74:75], v[124:125] op_sel_hi:[0,1,1]
	v_add_f32_dpp v158, v158, v158 row_half_mirror row_mask:0xf bank_mask:0xf bound_ctrl:1
	v_pk_fma_f32 v[122:123], v[156:157], v[76:77], v[122:123] op_sel_hi:[0,1,1]
	v_pk_fma_f32 v[120:121], v[156:157], v[78:79], v[120:121] op_sel_hi:[0,1,1]
	v_cndmask_b32_e64 v94, v94, v158, s[6:7]
	ds_read_b128 v[64:67], v154 offset:29952
	ds_read_b128 v[68:71], v154 offset:29968
	ds_read_b128 v[56:59], v154 offset:29696
	ds_read_b128 v[60:63], v154 offset:29712
	ds_read_b128 v[72:75], v154 offset:30208
	ds_read_b128 v[76:79], v154 offset:30224
	s_waitcnt lgkmcnt(6)
	v_pk_mul_f32 v[156:157], v[24:25], v[126:127]
	v_pk_mul_f32 v[90:91], v[28:29], v[122:123]
	v_pk_mul_f32 v[158:159], v[40:41], v[126:127]
	v_pk_fma_f32 v[156:157], v[124:125], v[26:27], v[156:157]
	v_pk_fma_f32 v[90:91], v[120:121], v[30:31], v[90:91]
	v_pk_fma_f32 v[158:159], v[124:125], v[42:43], v[158:159]
	v_pk_fma_f32 v[126:127], v[98:99], v[16:17], v[126:127] op_sel_hi:[0,1,1]
	v_pk_fma_f32 v[158:159], v[122:123], v[44:45], v[158:159]
	v_pk_fma_f32 v[124:125], v[98:99], v[18:19], v[124:125] op_sel_hi:[0,1,1]
	v_pk_add_f32 v[156:157], v[156:157], v[90:91]
	v_pk_fma_f32 v[158:159], v[120:121], v[46:47], v[158:159]
	v_add_f32_e32 v155, v156, v157
	v_pk_fma_f32 v[122:123], v[98:99], v[20:21], v[122:123] op_sel_hi:[0,1,1]
	v_pk_fma_f32 v[120:121], v[98:99], v[22:23], v[120:121] op_sel_hi:[0,1,1]
	ds_read_b128 v[40:43], v154 offset:29184
	ds_read_b128 v[44:47], v154 offset:29200
	v_add_f32_e32 v158, v158, v159
	v_add_f32_dpp v155, v155, v155 quad_perm:[1,0,3,2] row_mask:0xf bank_mask:0xf bound_ctrl:1
	s_mov_b32 s6, 0x2020202
	s_mov_b32 s7, 0x2020202
	v_add_f32_dpp v158, v158, v158 quad_perm:[1,0,3,2] row_mask:0xf bank_mask:0xf bound_ctrl:1
	v_add_f32_dpp v155, v155, v155 quad_perm:[2,3,0,1] row_mask:0xf bank_mask:0xf bound_ctrl:1
	s_nop 0
	v_add_f32_dpp v158, v158, v158 quad_perm:[2,3,0,1] row_mask:0xf bank_mask:0xf bound_ctrl:1
	v_add_f32_dpp v156, v155, v155 row_half_mirror row_mask:0xf bank_mask:0xf bound_ctrl:1
	v_pk_fma_f32 v[126:127], v[156:157], v[32:33], v[126:127] op_sel_hi:[0,1,1]
	v_pk_fma_f32 v[124:125], v[156:157], v[34:35], v[124:125] op_sel_hi:[0,1,1]
	v_add_f32_dpp v158, v158, v158 row_half_mirror row_mask:0xf bank_mask:0xf bound_ctrl:1
	v_pk_fma_f32 v[122:123], v[156:157], v[36:37], v[122:123] op_sel_hi:[0,1,1]
	v_pk_fma_f32 v[120:121], v[156:157], v[38:39], v[120:121] op_sel_hi:[0,1,1]
	v_cndmask_b32_e64 v94, v94, v158, s[6:7]
	ds_read_b128 v[24:27], v154 offset:31488
	ds_read_b128 v[28:31], v154 offset:31504
	ds_read_b128 v[16:19], v154 offset:31232
	ds_read_b128 v[20:23], v154 offset:31248
	ds_read_b128 v[32:35], v154 offset:31744
	ds_read_b128 v[36:39], v154 offset:31760
	ds_read2st64_b32 v[92:93], v153 offset0:125 offset1:131
	s_waitcnt lgkmcnt(7)
; #define LAS __attribute__((address_space(3)))
; DI unsigned pack2(float lo, float hi) { f32x2 v = {lo, hi}; return __builtin_bit_cast(unsigned, __builtin_convertvector(v, bf16x2_t)); }
; DI void scan_item(PP p, int l, int item, LAS unsigned char* lds) {
;     ...
;     for (int c = 0; c < NCH; ++c) {
;         if (wid >= 4) { if (c + 1 < NCH) { fill(c + 1); if (c + 2 < NCH) gl(c + 2); } }
;         else {
;             const LAS float* sp = buf + ((c & 1) * T) * 384;
;             f32x4 Ar0, Ar1, Aw0, Aw1, Ak0, Ak1, Aa0, Aa1, Ab0, Ab1; float Avv;
;             f32x4 Br0, Br1, Bw0, Bw1, Bk0, Bk1, Ba0, Ba1, Bb0, Bb1; float Bvv;
;             SC_LD(A, sp);
;             const ptrdiff_t ystep = dir ? -512 : 512;
;             u16* Yl = Yp + (size_t)steprow(b, dir, c * T) * 512 + (ptrdiff_t)ks * ystep;
; #pragma nounroll
;             for (int st = 0; st < T; st += 2) {
;                 SC_LD(B, sp + (st + 1) * 384);
;                 SC_STEP(A, st);
;                 if (st + 2 < T) SC_LD(A, sp + (st + 2) * 384);
;                 SC_STEP(B, st + 1);
;                 if ((st & 6) == 6) {
;                     const LAS float* rp = ypl + (ks * 68 - lane) + (lane & ~7);
;                     const f32x4 q0 = *(const LAS f32x4*)rp, q1 = *(const LAS f32x4*)(rp + 4);
;                     Yl[(ptrdiff_t)(st - 6) * ystep] = (u16)(pack2(((q0[0] + q0[1]) + (q0[2] + q0[3])) + ((q1[0] + q1[1]) + (q1[2] + q1[3])), 0.f) & 0xffffu);
;                 }
	v_pk_mul_f32 v[156:157], v[64:65], v[126:127]
	v_pk_mul_f32 v[90:91], v[68:69], v[122:123]
	v_pk_mul_f32 v[158:159], v[0:1], v[126:127]
	v_pk_fma_f32 v[156:157], v[124:125], v[66:67], v[156:157]
	v_pk_fma_f32 v[90:91], v[120:121], v[70:71], v[90:91]
	v_pk_fma_f32 v[158:159], v[124:125], v[2:3], v[158:159]
	v_pk_fma_f32 v[126:127], v[98:99], v[56:57], v[126:127] op_sel:[1,0,0] op_sel_hi:[1,1,1]
	v_pk_fma_f32 v[158:159], v[122:123], v[4:5], v[158:159]
	v_pk_fma_f32 v[124:125], v[98:99], v[58:59], v[124:125] op_sel:[1,0,0] op_sel_hi:[1,1,1]
	v_pk_add_f32 v[156:157], v[156:157], v[90:91]
	v_pk_fma_f32 v[158:159], v[120:121], v[6:7], v[158:159]
	v_add_f32_e32 v155, v156, v157
	v_pk_fma_f32 v[122:123], v[98:99], v[60:61], v[122:123] op_sel:[1,0,0] op_sel_hi:[1,1,1]
	v_pk_fma_f32 v[120:121], v[98:99], v[62:63], v[120:121] op_sel:[1,0,0] op_sel_hi:[1,1,1]
	ds_read_b128 v[0:3], v154 offset:30720
	ds_read_b128 v[4:7], v154 offset:30736
	v_add_f32_e32 v158, v158, v159
	v_add_f32_dpp v155, v155, v155 quad_perm:[1,0,3,2] row_mask:0xf bank_mask:0xf bound_ctrl:1
	s_mov_b32 s6, 0x4040404
	s_mov_b32 s7, 0x4040404
	v_add_f32_dpp v158, v158, v158 quad_perm:[1,0,3,2] row_mask:0xf bank_mask:0xf bound_ctrl:1
	v_add_f32_dpp v155, v155, v155 quad_perm:[2,3,0,1] row_mask:0xf bank_mask:0xf bound_ctrl:1
	s_nop 0
	v_add_f32_dpp v158, v158, v158 quad_perm:[2,3,0,1] row_mask:0xf bank_mask:0xf bound_ctrl:1
	v_add_f32_dpp v156, v155, v155 row_half_mirror row_mask:0xf bank_mask:0xf bound_ctrl:1
	v_pk_fma_f32 v[126:127], v[156:157], v[72:73], v[126:127] op_sel_hi:[0,1,1]
	v_pk_fma_f32 v[124:125], v[156:157], v[74:75], v[124:125] op_sel_hi:[0,1,1]
	v_add_f32_dpp v158, v158, v158 row_half_mirror row_mask:0xf bank_mask:0xf bound_ctrl:1
	v_pk_fma_f32 v[122:123], v[156:157], v[76:77], v[122:123] op_sel_hi:[0,1,1]
	v_pk_fma_f32 v[120:121], v[156:157], v[78:79], v[120:121] op_sel_hi:[0,1,1]
	v_cndmask_b32_e64 v94, v94, v158, s[6:7]
	ds_read_b128 v[64:67], v154 offset:33024
	ds_read_b128 v[68:71], v154 offset:33040
	ds_read_b128 v[56:59], v154 offset:32768
	ds_read_b128 v[60:63], v154 offset:32784
	ds_read_b128 v[72:75], v154 offset:33280
	ds_read_b128 v[76:79], v154 offset:33296
	s_waitcnt lgkmcnt(6)
	v_pk_mul_f32 v[156:157], v[24:25], v[126:127]
	v_pk_mul_f32 v[90:91], v[28:29], v[122:123]
	v_pk_mul_f32 v[158:159], v[40:41], v[126:127]
	v_pk_fma_f32 v[156:157], v[124:125], v[26:27], v[156:157]
	v_pk_fma_f32 v[90:91], v[120:121], v[30:31], v[90:91]
	v_pk_fma_f32 v[158:159], v[124:125], v[42:43], v[158:159]
	v_pk_fma_f32 v[126:127], v[92:93], v[16:17], v[126:127] op_sel_hi:[0,1,1]
	v_pk_fma_f32 v[158:159], v[122:123], v[44:45], v[158:159]
	v_pk_fma_f32 v[124:125], v[92:93], v[18:19], v[124:125] op_sel_hi:[0,1,1]
	v_pk_add_f32 v[156:157], v[156:157], v[90:91]
	v_pk_fma_f32 v[158:159], v[120:121], v[46:47], v[158:159]
	v_add_f32_e32 v155, v156, v157
	v_pk_fma_f32 v[122:123], v[92:93], v[20:21], v[122:123] op_sel_hi:[0,1,1]
	v_pk_fma_f32 v[120:121], v[92:93], v[22:23], v[120:121] op_sel_hi:[0,1,1]
	ds_read_b128 v[40:43], v154 offset:32256
	ds_read_b128 v[44:47], v154 offset:32272
	v_add_f32_e32 v158, v158, v159
	v_add_f32_dpp v155, v155, v155 quad_perm:[1,0,3,2] row_mask:0xf bank_mask:0xf bound_ctrl:1
	s_mov_b32 s6, 0x8080808
	s_mov_b32 s7, 0x8080808
	v_add_f32_dpp v158, v158, v158 quad_perm:[1,0,3,2] row_mask:0xf bank_mask:0xf bound_ctrl:1
	v_add_f32_dpp v155, v155, v155 quad_perm:[2,3,0,1] row_mask:0xf bank_mask:0xf bound_ctrl:1
	s_nop 0
	v_add_f32_dpp v158, v158, v158 quad_perm:[2,3,0,1] row_mask:0xf bank_mask:0xf bound_ctrl:1
	v_add_f32_dpp v156, v155, v155 row_half_mirror row_mask:0xf bank_mask:0xf bound_ctrl:1
	v_pk_fma_f32 v[126:127], v[156:157], v[32:33], v[126:127] op_sel_hi:[0,1,1]
	v_pk_fma_f32 v[124:125], v[156:157], v[34:35], v[124:125] op_sel_hi:[0,1,1]
	v_add_f32_dpp v158, v158, v158 row_half_mirror row_mask:0xf bank_mask:0xf bound_ctrl:1
	v_pk_fma_f32 v[122:123], v[156:157], v[36:37], v[122:123] op_sel_hi:[0,1,1]
	v_pk_fma_f32 v[120:121], v[156:157], v[38:39], v[120:121] op_sel_hi:[0,1,1]
	v_cndmask_b32_e64 v94, v94, v158, s[6:7]
	ds_read_b128 v[24:27], v154 offset:34560
	ds_read_b128 v[28:31], v154 offset:34576
	ds_read_b128 v[16:19], v154 offset:34304
	ds_read_b128 v[20:23], v154 offset:34320
	ds_read_b128 v[32:35], v154 offset:34816
	ds_read_b128 v[36:39], v154 offset:34832
	ds_read2st64_b32 v[98:99], v153 offset0:137 offset1:143
	s_waitcnt lgkmcnt(7)
	v_pk_mul_f32 v[156:157], v[64:65], v[126:127]
	v_pk_mul_f32 v[90:91], v[68:69], v[122:123]
	v_pk_mul_f32 v[158:159], v[0:1], v[126:127]
	v_pk_fma_f32 v[156:157], v[124:125], v[66:67], v[156:157]
	v_pk_fma_f32 v[90:91], v[120:121], v[70:71], v[90:91]
	v_pk_fma_f32 v[158:159], v[124:125], v[2:3], v[158:159]
	v_pk_fma_f32 v[126:127], v[92:93], v[56:57], v[126:127] op_sel:[1,0,0] op_sel_hi:[1,1,1]
	v_pk_fma_f32 v[158:159], v[122:123], v[4:5], v[158:159]
	v_pk_fma_f32 v[124:125], v[92:93], v[58:59], v[124:125] op_sel:[1,0,0] op_sel_hi:[1,1,1]
	v_pk_add_f32 v[156:157], v[156:157], v[90:91]
	v_pk_fma_f32 v[158:159], v[120:121], v[6:7], v[158:159]
	v_add_f32_e32 v155, v156, v157
	v_pk_fma_f32 v[122:123], v[92:93], v[60:61], v[122:123] op_sel:[1,0,0] op_sel_hi:[1,1,1]
	v_pk_fma_f32 v[120:121], v[92:93], v[62:63], v[120:121] op_sel:[1,0,0] op_sel_hi:[1,1,1]
	ds_read_b128 v[0:3], v154 offset:33792
	ds_read_b128 v[4:7], v154 offset:33808
	v_add_f32_e32 v158, v158, v159
	v_add_f32_dpp v155, v155, v155 quad_perm:[1,0,3,2] row_mask:0xf bank_mask:0xf bound_ctrl:1
	s_mov_b32 s6, 0x10101010
	s_mov_b32 s7, 0x10101010
	v_add_f32_dpp v158, v158, v158 quad_perm:[1,0,3,2] row_mask:0xf bank_mask:0xf bound_ctrl:1
	v_add_f32_dpp v155, v155, v155 quad_perm:[2,3,0,1] row_mask:0xf bank_mask:0xf bound_ctrl:1
	s_nop 0
	v_add_f32_dpp v158, v158, v158 quad_perm:[2,3,0,1] row_mask:0xf bank_mask:0xf bound_ctrl:1
	v_add_f32_dpp v156, v155, v155 row_half_mirror row_mask:0xf bank_mask:0xf bound_ctrl:1
	v_pk_fma_f32 v[126:127], v[156:157], v[72:73], v[126:127] op_sel_hi:[0,1,1]
	v_pk_fma_f32 v[124:125], v[156:157], v[74:75], v[124:125] op_sel_hi:[0,1,1]
	v_add_f32_dpp v158, v158, v158 row_half_mirror row_mask:0xf bank_mask:0xf bound_ctrl:1
	v_pk_fma_f32 v[122:123], v[156:157], v[76:77], v[122:123] op_sel_hi:[0,1,1]
	v_pk_fma_f32 v[120:121], v[156:157], v[78:79], v[120:121] op_sel_hi:[0,1,1]
	v_cndmask_b32_e64 v94, v94, v158, s[6:7]
	ds_read_b128 v[64:67], v154 offset:36096
	ds_read_b128 v[68:71], v154 offset:36112
	ds_read_b128 v[56:59], v154 offset:35840
	ds_read_b128 v[60:63], v154 offset:35856
	ds_read_b128 v[72:75], v154 offset:36352
	ds_read_b128 v[76:79], v154 offset:36368
	ds_read_b128 v[48:51], v154 offset:35584
	ds_read_b128 v[52:55], v154 offset:35600
	s_waitcnt lgkmcnt(8)
; #define LAS __attribute__((address_space(3)))
; DI unsigned pack2(float lo, float hi) { f32x2 v = {lo, hi}; return __builtin_bit_cast(unsigned, __builtin_convertvector(v, bf16x2_t)); }
; DI void scan_item(PP p, int l, int item, LAS unsigned char* lds) {
;     ...
;     for (int c = 0; c < NCH; ++c) {
;         if (wid >= 4) { if (c + 1 < NCH) { fill(c + 1); if (c + 2 < NCH) gl(c + 2); } }
;         else {
;             const LAS float* sp = buf + ((c & 1) * T) * 384;
;             f32x4 Ar0, Ar1, Aw0, Aw1, Ak0, Ak1, Aa0, Aa1, Ab0, Ab1; float Avv;
;             f32x4 Br0, Br1, Bw0, Bw1, Bk0, Bk1, Ba0, Ba1, Bb0, Bb1; float Bvv;
;             SC_LD(A, sp);
;             const ptrdiff_t ystep = dir ? -512 : 512;
;             u16* Yl = Yp + (size_t)steprow(b, dir, c * T) * 512 + (ptrdiff_t)ks * ystep;
; #pragma nounroll
;             for (int st = 0; st < T; st += 2) {
;                 SC_LD(B, sp + (st + 1) * 384);
;                 SC_STEP(A, st);
;                 if (st + 2 < T) SC_LD(A, sp + (st + 2) * 384);
;                 SC_STEP(B, st + 1);
;                 if ((st & 6) == 6) {
;                     const LAS float* rp = ypl + (ks * 68 - lane) + (lane & ~7);
;                     const f32x4 q0 = *(const LAS f32x4*)rp, q1 = *(const LAS f32x4*)(rp + 4);
;                     Yl[(ptrdiff_t)(st - 6) * ystep] = (u16)(pack2(((q0[0] + q0[1]) + (q0[2] + q0[3])) + ((q1[0] + q1[1]) + (q1[2] + q1[3])), 0.f) & 0xffffu);
;                 }
	v_pk_mul_f32 v[156:157], v[24:25], v[126:127]
	v_pk_mul_f32 v[90:91], v[28:29], v[122:123]
	v_pk_mul_f32 v[158:159], v[40:41], v[126:127]
	v_pk_fma_f32 v[156:157], v[124:125], v[26:27], v[156:157]
	v_pk_fma_f32 v[90:91], v[120:121], v[30:31], v[90:91]
	v_pk_fma_f32 v[158:159], v[124:125], v[42:43], v[158:159]
	v_pk_fma_f32 v[126:127], v[98:99], v[16:17], v[126:127] op_sel_hi:[0,1,1]
	v_pk_fma_f32 v[158:159], v[122:123], v[44:45], v[158:159]
	v_pk_fma_f32 v[124:125], v[98:99], v[18:19], v[124:125] op_sel_hi:[0,1,1]
	v_pk_add_f32 v[156:157], v[156:157], v[90:91]
	v_pk_fma_f32 v[158:159], v[120:121], v[46:47], v[158:159]
	v_add_f32_e32 v155, v156, v157
	v_pk_fma_f32 v[122:123], v[98:99], v[20:21], v[122:123] op_sel_hi:[0,1,1]
	v_pk_fma_f32 v[120:121], v[98:99], v[22:23], v[120:121] op_sel_hi:[0,1,1]
	ds_read_b128 v[40:43], v154 offset:35328
	ds_read_b128 v[44:47], v154 offset:35344
	v_add_f32_e32 v158, v158, v159
	v_add_f32_dpp v155, v155, v155 quad_perm:[1,0,3,2] row_mask:0xf bank_mask:0xf bound_ctrl:1
	s_mov_b32 s6, 0x20202020
	s_mov_b32 s7, 0x20202020
	v_add_f32_dpp v158, v158, v158 quad_perm:[1,0,3,2] row_mask:0xf bank_mask:0xf bound_ctrl:1
	v_add_f32_dpp v155, v155, v155 quad_perm:[2,3,0,1] row_mask:0xf bank_mask:0xf bound_ctrl:1
	s_nop 0
	v_add_f32_dpp v158, v158, v158 quad_perm:[2,3,0,1] row_mask:0xf bank_mask:0xf bound_ctrl:1
	v_add_f32_dpp v156, v155, v155 row_half_mirror row_mask:0xf bank_mask:0xf bound_ctrl:1
	v_pk_fma_f32 v[126:127], v[156:157], v[32:33], v[126:127] op_sel_hi:[0,1,1]
	v_pk_fma_f32 v[124:125], v[156:157], v[34:35], v[124:125] op_sel_hi:[0,1,1]
	v_add_f32_dpp v158, v158, v158 row_half_mirror row_mask:0xf bank_mask:0xf bound_ctrl:1
	v_pk_fma_f32 v[122:123], v[156:157], v[36:37], v[122:123] op_sel_hi:[0,1,1]
	v_pk_fma_f32 v[120:121], v[156:157], v[38:39], v[120:121] op_sel_hi:[0,1,1]
	v_cndmask_b32_e64 v94, v94, v158, s[6:7]
	ds_read_b128 v[24:27], v154 offset:37632
	ds_read_b128 v[28:31], v154 offset:37648
	ds_read_b128 v[16:19], v154 offset:37376
	ds_read_b128 v[20:23], v154 offset:37392
	ds_read_b128 v[32:35], v154 offset:37888
	ds_read_b128 v[36:39], v154 offset:37904
	ds_read2st64_b32 v[92:93], v153 offset0:149 offset1:155
	s_waitcnt lgkmcnt(7)
	v_pk_mul_f32 v[156:157], v[64:65], v[126:127]
	v_pk_mul_f32 v[90:91], v[68:69], v[122:123]
	v_pk_mul_f32 v[158:159], v[0:1], v[126:127]
	v_pk_fma_f32 v[156:157], v[124:125], v[66:67], v[156:157]
	v_pk_fma_f32 v[90:91], v[120:121], v[70:71], v[90:91]
	v_pk_fma_f32 v[158:159], v[124:125], v[2:3], v[158:159]
	v_pk_fma_f32 v[126:127], v[98:99], v[56:57], v[126:127] op_sel:[1,0,0] op_sel_hi:[1,1,1]
	v_pk_fma_f32 v[158:159], v[122:123], v[4:5], v[158:159]
	v_pk_fma_f32 v[124:125], v[98:99], v[58:59], v[124:125] op_sel:[1,0,0] op_sel_hi:[1,1,1]
	v_pk_add_f32 v[156:157], v[156:157], v[90:91]
	v_pk_fma_f32 v[158:159], v[120:121], v[6:7], v[158:159]
	v_add_f32_e32 v155, v156, v157
	v_pk_fma_f32 v[122:123], v[98:99], v[60:61], v[122:123] op_sel:[1,0,0] op_sel_hi:[1,1,1]
	v_pk_fma_f32 v[120:121], v[98:99], v[62:63], v[120:121] op_sel:[1,0,0] op_sel_hi:[1,1,1]
	ds_read_b128 v[0:3], v154 offset:36864
	ds_read_b128 v[4:7], v154 offset:36880
	v_add_f32_e32 v158, v158, v159
	v_add_f32_dpp v155, v155, v155 quad_perm:[1,0,3,2] row_mask:0xf bank_mask:0xf bound_ctrl:1
	s_mov_b32 s6, 0x40404040
	s_mov_b32 s7, 0x40404040
	v_add_f32_dpp v158, v158, v158 quad_perm:[1,0,3,2] row_mask:0xf bank_mask:0xf bound_ctrl:1
	v_add_f32_dpp v155, v155, v155 quad_perm:[2,3,0,1] row_mask:0xf bank_mask:0xf bound_ctrl:1
	s_nop 0
	v_add_f32_dpp v158, v158, v158 quad_perm:[2,3,0,1] row_mask:0xf bank_mask:0xf bound_ctrl:1
	v_add_f32_dpp v156, v155, v155 row_half_mirror row_mask:0xf bank_mask:0xf bound_ctrl:1
	v_pk_fma_f32 v[126:127], v[156:157], v[72:73], v[126:127] op_sel_hi:[0,1,1]
	v_pk_fma_f32 v[124:125], v[156:157], v[74:75], v[124:125] op_sel_hi:[0,1,1]
	v_add_f32_dpp v158, v158, v158 row_half_mirror row_mask:0xf bank_mask:0xf bound_ctrl:1
	v_pk_fma_f32 v[122:123], v[156:157], v[76:77], v[122:123] op_sel_hi:[0,1,1]
	v_pk_fma_f32 v[120:121], v[156:157], v[78:79], v[120:121] op_sel_hi:[0,1,1]
	v_cndmask_b32_e64 v94, v94, v158, s[6:7]
	v_pk_mul_f32 v[158:159], v[40:41], v[126:127]
	s_nop 0
	v_pk_fma_f32 v[158:159], v[124:125], v[42:43], v[158:159]
	s_nop 0
	v_pk_fma_f32 v[158:159], v[122:123], v[44:45], v[158:159]
	s_nop 0
	v_pk_fma_f32 v[158:159], v[120:121], v[46:47], v[158:159]
	s_nop 0
	v_add_f32_e32 v158, v158, v159
	s_mov_b32 s6, 0x80808080
	s_mov_b32 s7, 0x80808080
	v_add_f32_dpp v158, v158, v158 quad_perm:[1,0,3,2] row_mask:0xf bank_mask:0xf bound_ctrl:1
	s_nop 1
	v_add_f32_dpp v158, v158, v158 quad_perm:[2,3,0,1] row_mask:0xf bank_mask:0xf bound_ctrl:1
	s_nop 1
	v_add_f32_dpp v158, v158, v158 row_half_mirror row_mask:0xf bank_mask:0xf bound_ctrl:1
	v_pk_mul_f32 v[126:127], v[48:49], v[126:127]
	v_pk_mul_f32 v[124:125], v[50:51], v[124:125]
	v_pk_mul_f32 v[122:123], v[52:53], v[122:123]
	v_pk_mul_f32 v[120:121], v[54:55], v[120:121]
	v_cndmask_b32_e64 v94, v94, v158, s[6:7]
	ds_read_b128 v[40:43], v154 offset:38400
	ds_read_b128 v[44:47], v154 offset:38416
	ds_read_b128 v[64:67], v154 offset:39168
	ds_read_b128 v[68:71], v154 offset:39184
	ds_read_b128 v[56:59], v154 offset:38912
	ds_read_b128 v[60:63], v154 offset:38928
	ds_read_b128 v[72:75], v154 offset:39424
	ds_read_b128 v[76:79], v154 offset:39440
	s_waitcnt lgkmcnt(8)
; #define LAS __attribute__((address_space(3)))
; DI unsigned pack2(float lo, float hi) { f32x2 v = {lo, hi}; return __builtin_bit_cast(unsigned, __builtin_convertvector(v, bf16x2_t)); }
; DI void scan_item(PP p, int l, int item, LAS unsigned char* lds) {
;     ...
;     for (int c = 0; c < NCH; ++c) {
;         if (wid >= 4) { if (c + 1 < NCH) { fill(c + 1); if (c + 2 < NCH) gl(c + 2); } }
;         else {
;             const LAS float* sp = buf + ((c & 1) * T) * 384;
;             f32x4 Ar0, Ar1, Aw0, Aw1, Ak0, Ak1, Aa0, Aa1, Ab0, Ab1; float Avv;
;             f32x4 Br0, Br1, Bw0, Bw1, Bk0, Bk1, Ba0, Ba1, Bb0, Bb1; float Bvv;
;             SC_LD(A, sp);
;             const ptrdiff_t ystep = dir ? -512 : 512;
;             u16* Yl = Yp + (size_t)steprow(b, dir, c * T) * 512 + (ptrdiff_t)ks * ystep;
; #pragma nounroll
;             for (int st = 0; st < T; st += 2) {
;                 SC_LD(B, sp + (st + 1) * 384);
;                 SC_STEP(A, st);
;                 if (st + 2 < T) SC_LD(A, sp + (st + 2) * 384);
;                 SC_STEP(B, st + 1);
;                 if ((st & 6) == 6) {
;                     const LAS float* rp = ypl + (ks * 68 - lane) + (lane & ~7);
;                     const f32x4 q0 = *(const LAS f32x4*)rp, q1 = *(const LAS f32x4*)(rp + 4);
;                     Yl[(ptrdiff_t)(st - 6) * ystep] = (u16)(pack2(((q0[0] + q0[1]) + (q0[2] + q0[3])) + ((q1[0] + q1[1]) + (q1[2] + q1[3])), 0.f) & 0xffffu);
;                 }
	v_pk_mul_f32 v[156:157], v[24:25], v[126:127]
	v_pk_mul_f32 v[90:91], v[28:29], v[122:123]
	v_pk_fma_f32 v[126:127], v[92:93], v[16:17], v[126:127] op_sel_hi:[0,1,1]
	v_pk_fma_f32 v[156:157], v[124:125], v[26:27], v[156:157]
	v_pk_fma_f32 v[90:91], v[120:121], v[30:31], v[90:91]
	v_pk_fma_f32 v[124:125], v[92:93], v[18:19], v[124:125] op_sel_hi:[0,1,1]
	v_pk_fma_f32 v[122:123], v[92:93], v[20:21], v[122:123] op_sel_hi:[0,1,1]
	v_pk_add_f32 v[156:157], v[156:157], v[90:91]
	v_pk_fma_f32 v[120:121], v[92:93], v[22:23], v[120:121] op_sel_hi:[0,1,1]
	v_add_f32_e32 v155, v156, v157
	s_nop 1
	v_add_f32_dpp v155, v155, v155 quad_perm:[1,0,3,2] row_mask:0xf bank_mask:0xf bound_ctrl:1
	s_nop 1
	v_add_f32_dpp v155, v155, v155 quad_perm:[2,3,0,1] row_mask:0xf bank_mask:0xf bound_ctrl:1
	s_nop 1
	v_add_f32_dpp v156, v155, v155 row_half_mirror row_mask:0xf bank_mask:0xf bound_ctrl:1
	v_pk_fma_f32 v[126:127], v[156:157], v[32:33], v[126:127] op_sel_hi:[0,1,1]
	v_pk_fma_f32 v[124:125], v[156:157], v[34:35], v[124:125] op_sel_hi:[0,1,1]
	v_pk_fma_f32 v[122:123], v[156:157], v[36:37], v[122:123] op_sel_hi:[0,1,1]
	v_pk_fma_f32 v[120:121], v[156:157], v[38:39], v[120:121] op_sel_hi:[0,1,1]
	v_cvt_pk_bf16_f32 v82, v94, v94
	global_store_short v[118:119], v82, off
	v_lshl_add_u64 v[118:119], s[8:9], 0, v[118:119]
	ds_read_b128 v[24:27], v154 offset:40704
	ds_read_b128 v[28:31], v154 offset:40720
	ds_read_b128 v[16:19], v154 offset:40448
	ds_read_b128 v[20:23], v154 offset:40464
	ds_read_b128 v[32:35], v154 offset:40960
	ds_read_b128 v[36:39], v154 offset:40976
	ds_read2st64_b32 v[98:99], v153 offset0:161 offset1:167
	s_waitcnt lgkmcnt(7)
	v_pk_mul_f32 v[156:157], v[64:65], v[126:127]
	v_pk_mul_f32 v[90:91], v[68:69], v[122:123]
	v_pk_mul_f32 v[158:159], v[0:1], v[126:127]
	v_pk_fma_f32 v[156:157], v[124:125], v[66:67], v[156:157]
	v_pk_fma_f32 v[90:91], v[120:121], v[70:71], v[90:91]
	v_pk_fma_f32 v[158:159], v[124:125], v[2:3], v[158:159]
	v_pk_fma_f32 v[126:127], v[92:93], v[56:57], v[126:127] op_sel:[1,0,0] op_sel_hi:[1,1,1]
	v_pk_fma_f32 v[158:159], v[122:123], v[4:5], v[158:159]
	v_pk_fma_f32 v[124:125], v[92:93], v[58:59], v[124:125] op_sel:[1,0,0] op_sel_hi:[1,1,1]
	v_pk_add_f32 v[156:157], v[156:157], v[90:91]
	v_pk_fma_f32 v[158:159], v[120:121], v[6:7], v[158:159]
	v_add_f32_e32 v155, v156, v157
	v_pk_fma_f32 v[122:123], v[92:93], v[60:61], v[122:123] op_sel:[1,0,0] op_sel_hi:[1,1,1]
	v_pk_fma_f32 v[120:121], v[92:93], v[62:63], v[120:121] op_sel:[1,0,0] op_sel_hi:[1,1,1]
	ds_read_b128 v[0:3], v154 offset:39936
	ds_read_b128 v[4:7], v154 offset:39952
	v_add_f32_e32 v158, v158, v159
	v_add_f32_dpp v155, v155, v155 quad_perm:[1,0,3,2] row_mask:0xf bank_mask:0xf bound_ctrl:1
	s_mov_b32 s6, 0x1010101
	s_mov_b32 s7, 0x1010101
	v_add_f32_dpp v158, v158, v158 quad_perm:[1,0,3,2] row_mask:0xf bank_mask:0xf bound_ctrl:1
	v_add_f32_dpp v155, v155, v155 quad_perm:[2,3,0,1] row_mask:0xf bank_mask:0xf bound_ctrl:1
	s_nop 0
	v_add_f32_dpp v158, v158, v158 quad_perm:[2,3,0,1] row_mask:0xf bank_mask:0xf bound_ctrl:1
	v_add_f32_dpp v156, v155, v155 row_half_mirror row_mask:0xf bank_mask:0xf bound_ctrl:1
	v_pk_fma_f32 v[126:127], v[156:157], v[72:73], v[126:127] op_sel_hi:[0,1,1]
	v_pk_fma_f32 v[124:125], v[156:157], v[74:75], v[124:125] op_sel_hi:[0,1,1]
	v_add_f32_dpp v158, v158, v158 row_half_mirror row_mask:0xf bank_mask:0xf bound_ctrl:1
	v_pk_fma_f32 v[122:123], v[156:157], v[76:77], v[122:123] op_sel_hi:[0,1,1]
	v_pk_fma_f32 v[120:121], v[156:157], v[78:79], v[120:121] op_sel_hi:[0,1,1]
	v_cndmask_b32_e64 v94, v94, v158, s[6:7]
	ds_read_b128 v[64:67], v154 offset:42240
	ds_read_b128 v[68:71], v154 offset:42256
	ds_read_b128 v[56:59], v154 offset:41984
	ds_read_b128 v[60:63], v154 offset:42000
	ds_read_b128 v[72:75], v154 offset:42496
	ds_read_b128 v[76:79], v154 offset:42512
	s_waitcnt lgkmcnt(6)
	v_pk_mul_f32 v[156:157], v[24:25], v[126:127]
	v_pk_mul_f32 v[90:91], v[28:29], v[122:123]
	v_pk_mul_f32 v[158:159], v[40:41], v[126:127]
	v_pk_fma_f32 v[156:157], v[124:125], v[26:27], v[156:157]
	v_pk_fma_f32 v[90:91], v[120:121], v[30:31], v[90:91]
	v_pk_fma_f32 v[158:159], v[124:125], v[42:43], v[158:159]
	v_pk_fma_f32 v[126:127], v[98:99], v[16:17], v[126:127] op_sel_hi:[0,1,1]
	v_pk_fma_f32 v[158:159], v[122:123], v[44:45], v[158:159]
	v_pk_fma_f32 v[124:125], v[98:99], v[18:19], v[124:125] op_sel_hi:[0,1,1]
	v_pk_add_f32 v[156:157], v[156:157], v[90:91]
	v_pk_fma_f32 v[158:159], v[120:121], v[46:47], v[158:159]
	v_add_f32_e32 v155, v156, v157
	v_pk_fma_f32 v[122:123], v[98:99], v[20:21], v[122:123] op_sel_hi:[0,1,1]
	v_pk_fma_f32 v[120:121], v[98:99], v[22:23], v[120:121] op_sel_hi:[0,1,1]
	ds_read_b128 v[40:43], v154 offset:41472
	ds_read_b128 v[44:47], v154 offset:41488
	v_add_f32_e32 v158, v158, v159
	v_add_f32_dpp v155, v155, v155 quad_perm:[1,0,3,2] row_mask:0xf bank_mask:0xf bound_ctrl:1
	s_mov_b32 s6, 0x2020202
	s_mov_b32 s7, 0x2020202
	v_add_f32_dpp v158, v158, v158 quad_perm:[1,0,3,2] row_mask:0xf bank_mask:0xf bound_ctrl:1
	v_add_f32_dpp v155, v155, v155 quad_perm:[2,3,0,1] row_mask:0xf bank_mask:0xf bound_ctrl:1
	s_nop 0
	v_add_f32_dpp v158, v158, v158 quad_perm:[2,3,0,1] row_mask:0xf bank_mask:0xf bound_ctrl:1
	v_add_f32_dpp v156, v155, v155 row_half_mirror row_mask:0xf bank_mask:0xf bound_ctrl:1
	v_pk_fma_f32 v[126:127], v[156:157], v[32:33], v[126:127] op_sel_hi:[0,1,1]
	v_pk_fma_f32 v[124:125], v[156:157], v[34:35], v[124:125] op_sel_hi:[0,1,1]
	v_add_f32_dpp v158, v158, v158 row_half_mirror row_mask:0xf bank_mask:0xf bound_ctrl:1
	v_pk_fma_f32 v[122:123], v[156:157], v[36:37], v[122:123] op_sel_hi:[0,1,1]
	v_pk_fma_f32 v[120:121], v[156:157], v[38:39], v[120:121] op_sel_hi:[0,1,1]
	v_cndmask_b32_e64 v94, v94, v158, s[6:7]
	ds_read_b128 v[24:27], v154 offset:43776
	ds_read_b128 v[28:31], v154 offset:43792
	ds_read_b128 v[16:19], v154 offset:43520
	ds_read_b128 v[20:23], v154 offset:43536
	ds_read_b128 v[32:35], v154 offset:44032
	ds_read_b128 v[36:39], v154 offset:44048
	ds_read2st64_b32 v[92:93], v153 offset0:173 offset1:179
	s_waitcnt lgkmcnt(7)
; #define LAS __attribute__((address_space(3)))
; DI unsigned pack2(float lo, float hi) { f32x2 v = {lo, hi}; return __builtin_bit_cast(unsigned, __builtin_convertvector(v, bf16x2_t)); }
; DI void scan_item(PP p, int l, int item, LAS unsigned char* lds) {
;     ...
;     for (int c = 0; c < NCH; ++c) {
;         if (wid >= 4) { if (c + 1 < NCH) { fill(c + 1); if (c + 2 < NCH) gl(c + 2); } }
;         else {
;             const LAS float* sp = buf + ((c & 1) * T) * 384;
;             f32x4 Ar0, Ar1, Aw0, Aw1, Ak0, Ak1, Aa0, Aa1, Ab0, Ab1; float Avv;
;             f32x4 Br0, Br1, Bw0, Bw1, Bk0, Bk1, Ba0, Ba1, Bb0, Bb1; float Bvv;
;             SC_LD(A, sp);
;             const ptrdiff_t ystep = dir ? -512 : 512;
;             u16* Yl = Yp + (size_t)steprow(b, dir, c * T) * 512 + (ptrdiff_t)ks * ystep;
; #pragma nounroll
;             for (int st = 0; st < T; st += 2) {
;                 SC_LD(B, sp + (st + 1) * 384);
;                 SC_STEP(A, st);
;                 if (st + 2 < T) SC_LD(A, sp + (st + 2) * 384);
;                 SC_STEP(B, st + 1);
;                 if ((st & 6) == 6) {
;                     const LAS float* rp = ypl + (ks * 68 - lane) + (lane & ~7);
;                     const f32x4 q0 = *(const LAS f32x4*)rp, q1 = *(const LAS f32x4*)(rp + 4);
;                     Yl[(ptrdiff_t)(st - 6) * ystep] = (u16)(pack2(((q0[0] + q0[1]) + (q0[2] + q0[3])) + ((q1[0] + q1[1]) + (q1[2] + q1[3])), 0.f) & 0xffffu);
;                 }
	v_pk_mul_f32 v[156:157], v[64:65], v[126:127]
	v_pk_mul_f32 v[90:91], v[68:69], v[122:123]
	v_pk_mul_f32 v[158:159], v[0:1], v[126:127]
	v_pk_fma_f32 v[156:157], v[124:125], v[66:67], v[156:157]
	v_pk_fma_f32 v[90:91], v[120:121], v[70:71], v[90:91]
	v_pk_fma_f32 v[158:159], v[124:125], v[2:3], v[158:159]
	v_pk_fma_f32 v[126:127], v[98:99], v[56:57], v[126:127] op_sel:[1,0,0] op_sel_hi:[1,1,1]
	v_pk_fma_f32 v[158:159], v[122:123], v[4:5], v[158:159]
	v_pk_fma_f32 v[124:125], v[98:99], v[58:59], v[124:125] op_sel:[1,0,0] op_sel_hi:[1,1,1]
	v_pk_add_f32 v[156:157], v[156:157], v[90:91]
	v_pk_fma_f32 v[158:159], v[120:121], v[6:7], v[158:159]
	v_add_f32_e32 v155, v156, v157
	v_pk_fma_f32 v[122:123], v[98:99], v[60:61], v[122:123] op_sel:[1,0,0] op_sel_hi:[1,1,1]
	v_pk_fma_f32 v[120:121], v[98:99], v[62:63], v[120:121] op_sel:[1,0,0] op_sel_hi:[1,1,1]
	ds_read_b128 v[0:3], v154 offset:43008
	ds_read_b128 v[4:7], v154 offset:43024
	v_add_f32_e32 v158, v158, v159
	v_add_f32_dpp v155, v155, v155 quad_perm:[1,0,3,2] row_mask:0xf bank_mask:0xf bound_ctrl:1
	s_mov_b32 s6, 0x4040404
	s_mov_b32 s7, 0x4040404
	v_add_f32_dpp v158, v158, v158 quad_perm:[1,0,3,2] row_mask:0xf bank_mask:0xf bound_ctrl:1
	v_add_f32_dpp v155, v155, v155 quad_perm:[2,3,0,1] row_mask:0xf bank_mask:0xf bound_ctrl:1
	s_nop 0
	v_add_f32_dpp v158, v158, v158 quad_perm:[2,3,0,1] row_mask:0xf bank_mask:0xf bound_ctrl:1
	v_add_f32_dpp v156, v155, v155 row_half_mirror row_mask:0xf bank_mask:0xf bound_ctrl:1
	v_pk_fma_f32 v[126:127], v[156:157], v[72:73], v[126:127] op_sel_hi:[0,1,1]
	v_pk_fma_f32 v[124:125], v[156:157], v[74:75], v[124:125] op_sel_hi:[0,1,1]
	v_add_f32_dpp v158, v158, v158 row_half_mirror row_mask:0xf bank_mask:0xf bound_ctrl:1
	v_pk_fma_f32 v[122:123], v[156:157], v[76:77], v[122:123] op_sel_hi:[0,1,1]
	v_pk_fma_f32 v[120:121], v[156:157], v[78:79], v[120:121] op_sel_hi:[0,1,1]
	v_cndmask_b32_e64 v94, v94, v158, s[6:7]
	ds_read_b128 v[64:67], v154 offset:45312
	ds_read_b128 v[68:71], v154 offset:45328
	ds_read_b128 v[56:59], v154 offset:45056
	ds_read_b128 v[60:63], v154 offset:45072
	ds_read_b128 v[72:75], v154 offset:45568
	ds_read_b128 v[76:79], v154 offset:45584
	s_waitcnt lgkmcnt(6)
	v_pk_mul_f32 v[156:157], v[24:25], v[126:127]
	v_pk_mul_f32 v[90:91], v[28:29], v[122:123]
	v_pk_mul_f32 v[158:159], v[40:41], v[126:127]
	v_pk_fma_f32 v[156:157], v[124:125], v[26:27], v[156:157]
	v_pk_fma_f32 v[90:91], v[120:121], v[30:31], v[90:91]
	v_pk_fma_f32 v[158:159], v[124:125], v[42:43], v[158:159]
	v_pk_fma_f32 v[126:127], v[92:93], v[16:17], v[126:127] op_sel_hi:[0,1,1]
	v_pk_fma_f32 v[158:159], v[122:123], v[44:45], v[158:159]
	v_pk_fma_f32 v[124:125], v[92:93], v[18:19], v[124:125] op_sel_hi:[0,1,1]
	v_pk_add_f32 v[156:157], v[156:157], v[90:91]
	v_pk_fma_f32 v[158:159], v[120:121], v[46:47], v[158:159]
	v_add_f32_e32 v155, v156, v157
	v_pk_fma_f32 v[122:123], v[92:93], v[20:21], v[122:123] op_sel_hi:[0,1,1]
	v_pk_fma_f32 v[120:121], v[92:93], v[22:23], v[120:121] op_sel_hi:[0,1,1]
	ds_read_b128 v[40:43], v154 offset:44544
	ds_read_b128 v[44:47], v154 offset:44560
	v_add_f32_e32 v158, v158, v159
	v_add_f32_dpp v155, v155, v155 quad_perm:[1,0,3,2] row_mask:0xf bank_mask:0xf bound_ctrl:1
	s_mov_b32 s6, 0x8080808
	s_mov_b32 s7, 0x8080808
	v_add_f32_dpp v158, v158, v158 quad_perm:[1,0,3,2] row_mask:0xf bank_mask:0xf bound_ctrl:1
	v_add_f32_dpp v155, v155, v155 quad_perm:[2,3,0,1] row_mask:0xf bank_mask:0xf bound_ctrl:1
	s_nop 0
	v_add_f32_dpp v158, v158, v158 quad_perm:[2,3,0,1] row_mask:0xf bank_mask:0xf bound_ctrl:1
	v_add_f32_dpp v156, v155, v155 row_half_mirror row_mask:0xf bank_mask:0xf bound_ctrl:1
	v_pk_fma_f32 v[126:127], v[156:157], v[32:33], v[126:127] op_sel_hi:[0,1,1]
	v_pk_fma_f32 v[124:125], v[156:157], v[34:35], v[124:125] op_sel_hi:[0,1,1]
	v_add_f32_dpp v158, v158, v158 row_half_mirror row_mask:0xf bank_mask:0xf bound_ctrl:1
	v_pk_fma_f32 v[122:123], v[156:157], v[36:37], v[122:123] op_sel_hi:[0,1,1]
	v_pk_fma_f32 v[120:121], v[156:157], v[38:39], v[120:121] op_sel_hi:[0,1,1]
	v_cndmask_b32_e64 v94, v94, v158, s[6:7]
	ds_read_b128 v[24:27], v154 offset:46848
	ds_read_b128 v[28:31], v154 offset:46864
	ds_read_b128 v[16:19], v154 offset:46592
	ds_read_b128 v[20:23], v154 offset:46608
	ds_read_b128 v[32:35], v154 offset:47104
	ds_read_b128 v[36:39], v154 offset:47120
	ds_read2st64_b32 v[98:99], v153 offset0:185 offset1:191
	s_waitcnt lgkmcnt(7)
	v_pk_mul_f32 v[156:157], v[64:65], v[126:127]
	v_pk_mul_f32 v[90:91], v[68:69], v[122:123]
	v_pk_mul_f32 v[158:159], v[0:1], v[126:127]
	v_pk_fma_f32 v[156:157], v[124:125], v[66:67], v[156:157]
	v_pk_fma_f32 v[90:91], v[120:121], v[70:71], v[90:91]
	v_pk_fma_f32 v[158:159], v[124:125], v[2:3], v[158:159]
	v_pk_fma_f32 v[126:127], v[92:93], v[56:57], v[126:127] op_sel:[1,0,0] op_sel_hi:[1,1,1]
	v_pk_fma_f32 v[158:159], v[122:123], v[4:5], v[158:159]
	v_pk_fma_f32 v[124:125], v[92:93], v[58:59], v[124:125] op_sel:[1,0,0] op_sel_hi:[1,1,1]
	v_pk_add_f32 v[156:157], v[156:157], v[90:91]
	v_pk_fma_f32 v[158:159], v[120:121], v[6:7], v[158:159]
	v_add_f32_e32 v155, v156, v157
	v_pk_fma_f32 v[122:123], v[92:93], v[60:61], v[122:123] op_sel:[1,0,0] op_sel_hi:[1,1,1]
	v_pk_fma_f32 v[120:121], v[92:93], v[62:63], v[120:121] op_sel:[1,0,0] op_sel_hi:[1,1,1]
	ds_read_b128 v[0:3], v154 offset:46080
	ds_read_b128 v[4:7], v154 offset:46096
	v_add_f32_e32 v158, v158, v159
	v_add_f32_dpp v155, v155, v155 quad_perm:[1,0,3,2] row_mask:0xf bank_mask:0xf bound_ctrl:1
	s_mov_b32 s6, 0x10101010
	s_mov_b32 s7, 0x10101010
	v_add_f32_dpp v158, v158, v158 quad_perm:[1,0,3,2] row_mask:0xf bank_mask:0xf bound_ctrl:1
	v_add_f32_dpp v155, v155, v155 quad_perm:[2,3,0,1] row_mask:0xf bank_mask:0xf bound_ctrl:1
	s_nop 0
	v_add_f32_dpp v158, v158, v158 quad_perm:[2,3,0,1] row_mask:0xf bank_mask:0xf bound_ctrl:1
	v_add_f32_dpp v156, v155, v155 row_half_mirror row_mask:0xf bank_mask:0xf bound_ctrl:1
	v_pk_fma_f32 v[126:127], v[156:157], v[72:73], v[126:127] op_sel_hi:[0,1,1]
	v_pk_fma_f32 v[124:125], v[156:157], v[74:75], v[124:125] op_sel_hi:[0,1,1]
	v_add_f32_dpp v158, v158, v158 row_half_mirror row_mask:0xf bank_mask:0xf bound_ctrl:1
	v_pk_fma_f32 v[122:123], v[156:157], v[76:77], v[122:123] op_sel_hi:[0,1,1]
	v_pk_fma_f32 v[120:121], v[156:157], v[78:79], v[120:121] op_sel_hi:[0,1,1]
	v_cndmask_b32_e64 v94, v94, v158, s[6:7]
	ds_read_b128 v[64:67], v154 offset:48384
	ds_read_b128 v[68:71], v154 offset:48400
	ds_read_b128 v[56:59], v154 offset:48128
	ds_read_b128 v[60:63], v154 offset:48144
	ds_read_b128 v[72:75], v154 offset:48640
	ds_read_b128 v[76:79], v154 offset:48656
	ds_read_b128 v[48:51], v154 offset:47872
	ds_read_b128 v[52:55], v154 offset:47888
	s_waitcnt lgkmcnt(8)
; #define LAS __attribute__((address_space(3)))
; DI unsigned pack2(float lo, float hi) { f32x2 v = {lo, hi}; return __builtin_bit_cast(unsigned, __builtin_convertvector(v, bf16x2_t)); }
; DI void scan_item(PP p, int l, int item, LAS unsigned char* lds) {
;     ...
;     for (int c = 0; c < NCH; ++c) {
;         if (wid >= 4) { if (c + 1 < NCH) { fill(c + 1); if (c + 2 < NCH) gl(c + 2); } }
;         else {
;             const LAS float* sp = buf + ((c & 1) * T) * 384;
;             f32x4 Ar0, Ar1, Aw0, Aw1, Ak0, Ak1, Aa0, Aa1, Ab0, Ab1; float Avv;
;             f32x4 Br0, Br1, Bw0, Bw1, Bk0, Bk1, Ba0, Ba1, Bb0, Bb1; float Bvv;
;             SC_LD(A, sp);
;             const ptrdiff_t ystep = dir ? -512 : 512;
;             u16* Yl = Yp + (size_t)steprow(b, dir, c * T) * 512 + (ptrdiff_t)ks * ystep;
; #pragma nounroll
;             for (int st = 0; st < T; st += 2) {
;                 SC_LD(B, sp + (st + 1) * 384);
;                 SC_STEP(A, st);
;                 if (st + 2 < T) SC_LD(A, sp + (st + 2) * 384);
;                 SC_STEP(B, st + 1);
;                 if ((st & 6) == 6) {
;                     const LAS float* rp = ypl + (ks * 68 - lane) + (lane & ~7);
;                     const f32x4 q0 = *(const LAS f32x4*)rp, q1 = *(const LAS f32x4*)(rp + 4);
;                     Yl[(ptrdiff_t)(st - 6) * ystep] = (u16)(pack2(((q0[0] + q0[1]) + (q0[2] + q0[3])) + ((q1[0] + q1[1]) + (q1[2] + q1[3])), 0.f) & 0xffffu);
;                 }
	v_pk_mul_f32 v[156:157], v[24:25], v[126:127]
	v_pk_mul_f32 v[90:91], v[28:29], v[122:123]
	v_pk_mul_f32 v[158:159], v[40:41], v[126:127]
	v_pk_fma_f32 v[156:157], v[124:125], v[26:27], v[156:157]
	v_pk_fma_f32 v[90:91], v[120:121], v[30:31], v[90:91]
	v_pk_fma_f32 v[158:159], v[124:125], v[42:43], v[158:159]
	v_pk_fma_f32 v[126:127], v[98:99], v[16:17], v[126:127] op_sel_hi:[0,1,1]
	v_pk_fma_f32 v[158:159], v[122:123], v[44:45], v[158:159]
	v_pk_fma_f32 v[124:125], v[98:99], v[18:19], v[124:125] op_sel_hi:[0,1,1]
	v_pk_add_f32 v[156:157], v[156:157], v[90:91]
	v_pk_fma_f32 v[158:159], v[120:121], v[46:47], v[158:159]
	v_add_f32_e32 v155, v156, v157
	v_pk_fma_f32 v[122:123], v[98:99], v[20:21], v[122:123] op_sel_hi:[0,1,1]
	v_pk_fma_f32 v[120:121], v[98:99], v[22:23], v[120:121] op_sel_hi:[0,1,1]
	ds_read_b128 v[40:43], v154 offset:47616
	ds_read_b128 v[44:47], v154 offset:47632
	v_add_f32_e32 v158, v158, v159
	v_add_f32_dpp v155, v155, v155 quad_perm:[1,0,3,2] row_mask:0xf bank_mask:0xf bound_ctrl:1
	s_mov_b32 s6, 0x20202020
	s_mov_b32 s7, 0x20202020
	v_add_f32_dpp v158, v158, v158 quad_perm:[1,0,3,2] row_mask:0xf bank_mask:0xf bound_ctrl:1
	v_add_f32_dpp v155, v155, v155 quad_perm:[2,3,0,1] row_mask:0xf bank_mask:0xf bound_ctrl:1
	s_nop 0
	v_add_f32_dpp v158, v158, v158 quad_perm:[2,3,0,1] row_mask:0xf bank_mask:0xf bound_ctrl:1
	v_add_f32_dpp v156, v155, v155 row_half_mirror row_mask:0xf bank_mask:0xf bound_ctrl:1
	v_pk_fma_f32 v[126:127], v[156:157], v[32:33], v[126:127] op_sel_hi:[0,1,1]
	v_pk_fma_f32 v[124:125], v[156:157], v[34:35], v[124:125] op_sel_hi:[0,1,1]
	v_add_f32_dpp v158, v158, v158 row_half_mirror row_mask:0xf bank_mask:0xf bound_ctrl:1
	v_pk_fma_f32 v[122:123], v[156:157], v[36:37], v[122:123] op_sel_hi:[0,1,1]
	v_pk_fma_f32 v[120:121], v[156:157], v[38:39], v[120:121] op_sel_hi:[0,1,1]
	v_cndmask_b32_e64 v94, v94, v158, s[6:7]
	s_waitcnt lgkmcnt(0)
	v_pk_mul_f32 v[156:157], v[64:65], v[126:127]
	v_pk_mul_f32 v[90:91], v[68:69], v[122:123]
	v_pk_mul_f32 v[158:159], v[0:1], v[126:127]
	v_pk_fma_f32 v[156:157], v[124:125], v[66:67], v[156:157]
	v_pk_fma_f32 v[90:91], v[120:121], v[70:71], v[90:91]
	v_pk_fma_f32 v[158:159], v[124:125], v[2:3], v[158:159]
	v_pk_fma_f32 v[126:127], v[98:99], v[56:57], v[126:127] op_sel:[1,0,0] op_sel_hi:[1,1,1]
	v_pk_fma_f32 v[158:159], v[122:123], v[4:5], v[158:159]
	v_pk_fma_f32 v[124:125], v[98:99], v[58:59], v[124:125] op_sel:[1,0,0] op_sel_hi:[1,1,1]
	v_pk_add_f32 v[156:157], v[156:157], v[90:91]
	v_pk_fma_f32 v[158:159], v[120:121], v[6:7], v[158:159]
	v_add_f32_e32 v155, v156, v157
	v_pk_fma_f32 v[122:123], v[98:99], v[60:61], v[122:123] op_sel:[1,0,0] op_sel_hi:[1,1,1]
	v_pk_fma_f32 v[120:121], v[98:99], v[62:63], v[120:121] op_sel:[1,0,0] op_sel_hi:[1,1,1]
	v_add_f32_e32 v158, v158, v159
	v_add_f32_dpp v155, v155, v155 quad_perm:[1,0,3,2] row_mask:0xf bank_mask:0xf bound_ctrl:1
	s_mov_b32 s6, 0x40404040
	s_mov_b32 s7, 0x40404040
	v_add_f32_dpp v158, v158, v158 quad_perm:[1,0,3,2] row_mask:0xf bank_mask:0xf bound_ctrl:1
	v_add_f32_dpp v155, v155, v155 quad_perm:[2,3,0,1] row_mask:0xf bank_mask:0xf bound_ctrl:1
	s_nop 0
	v_add_f32_dpp v158, v158, v158 quad_perm:[2,3,0,1] row_mask:0xf bank_mask:0xf bound_ctrl:1
	v_add_f32_dpp v156, v155, v155 row_half_mirror row_mask:0xf bank_mask:0xf bound_ctrl:1
	v_pk_fma_f32 v[126:127], v[156:157], v[72:73], v[126:127] op_sel_hi:[0,1,1]
	v_pk_fma_f32 v[124:125], v[156:157], v[74:75], v[124:125] op_sel_hi:[0,1,1]
	v_add_f32_dpp v158, v158, v158 row_half_mirror row_mask:0xf bank_mask:0xf bound_ctrl:1
	v_pk_fma_f32 v[122:123], v[156:157], v[76:77], v[122:123] op_sel_hi:[0,1,1]
	v_pk_fma_f32 v[120:121], v[156:157], v[78:79], v[120:121] op_sel_hi:[0,1,1]
	v_cndmask_b32_e64 v94, v94, v158, s[6:7]
	v_pk_mul_f32 v[158:159], v[40:41], v[126:127]
	s_nop 0
	v_pk_fma_f32 v[158:159], v[124:125], v[42:43], v[158:159]
	s_nop 0
	v_pk_fma_f32 v[158:159], v[122:123], v[44:45], v[158:159]
	s_nop 0
	v_pk_fma_f32 v[158:159], v[120:121], v[46:47], v[158:159]
	s_nop 0
	v_add_f32_e32 v158, v158, v159
	s_mov_b32 s6, 0x80808080
	s_mov_b32 s7, 0x80808080
	v_add_f32_dpp v158, v158, v158 quad_perm:[1,0,3,2] row_mask:0xf bank_mask:0xf bound_ctrl:1
	s_nop 1
	v_add_f32_dpp v158, v158, v158 quad_perm:[2,3,0,1] row_mask:0xf bank_mask:0xf bound_ctrl:1
	s_nop 1
	v_add_f32_dpp v158, v158, v158 row_half_mirror row_mask:0xf bank_mask:0xf bound_ctrl:1
	v_pk_mul_f32 v[126:127], v[48:49], v[126:127]
	v_pk_mul_f32 v[124:125], v[50:51], v[124:125]
	v_pk_mul_f32 v[122:123], v[52:53], v[122:123]
	v_pk_mul_f32 v[120:121], v[54:55], v[120:121]
	v_cndmask_b32_e64 v94, v94, v158, s[6:7]
	v_cvt_pk_bf16_f32 v82, v94, v94
	global_store_short v[118:119], v82, off
	s_setprio 0
